# SwiGLU epilogues hand-scheduled, pipelined norm1 row loop, v_rsq in prep q/k norms, weight-set-2 transposes split between layer-0 gate-up tail and layer-1 w_in tail
# speedup vs baseline: 1.0167x; 1.0094x over previous
.LBB0_112:
	s_or_b64 exec, exec, s[0:1]
	s_mov_b64 s[4:5], s[34:35]
	s_mov_b64 s[8:9], s[34:35]
	s_mov_b64 s[10:11], s[34:35]
	s_waitcnt lgkmcnt(0)
	v_mov_b32_e32 v1, v0
	s_barrier
	s_nop 0
	v_readfirstlane_b32 s0, v1
	s_ashr_i32 s6, s0, 6
	s_add_i32 s0, s6, s90
	s_cmpk_gt_i32 s0, 0x47ff
	s_cbranch_scc1 .LBB0_117
	v_and_b32_e32 v2, 63, v1
	v_mbcnt_lo_u32_b32 v1, -1, 0
	v_mbcnt_hi_u32_b32 v3, -1, v1
	v_and_b32_e32 v1, 64, v3
	v_add_u32_e32 v4, 64, v1
	v_xor_b32_e32 v1, 1, v3
	v_cmp_lt_i32_e32 vcc, v1, v4
	v_xor_b32_e32 v5, 2, v3
	s_ashr_i32 s7, s6, 31
	v_cndmask_b32_e32 v1, v3, v1, vcc
	v_cmp_lt_i32_e32 vcc, v5, v4
	s_ashr_i32 s12, s90, 31
	s_add_u32 s6, s6, s90
	v_cndmask_b32_e32 v5, v3, v5, vcc
	v_lshlrev_b32_e32 v24, 2, v5
	v_xor_b32_e32 v5, 4, v3
	v_cmp_lt_i32_e32 vcc, v5, v4
	s_addc_u32 s7, s7, s12
	s_lshl_b64 s[12:13], s[6:7], 11
	v_cndmask_b32_e32 v5, v3, v5, vcc
	v_lshlrev_b32_e32 v25, 2, v5
	v_xor_b32_e32 v5, 8, v3
	v_cmp_lt_i32_e32 vcc, v5, v4
	v_mov_b32_e32 v19, 0
	v_lshlrev_b32_e32 v18, 4, v2
	v_cndmask_b32_e32 v5, v3, v5, vcc
	v_lshlrev_b32_e32 v26, 2, v5
	v_xor_b32_e32 v5, 16, v3
	v_cmp_lt_i32_e32 vcc, v5, v4
	s_add_u32 s8, s8, s12
	v_lshl_add_u64 v[20:21], s[28:29], 0, v[18:19]
	v_cndmask_b32_e32 v5, v3, v5, vcc
	v_lshlrev_b32_e32 v27, 2, v5
	v_xor_b32_e32 v5, 32, v3
	v_cmp_lt_i32_e32 vcc, v5, v4
	v_lshlrev_b32_e32 v18, 3, v2
	s_addc_u32 s9, s9, s13
	v_cndmask_b32_e32 v3, v3, v5, vcc
	v_lshl_add_u64 v[4:5], s[8:9], 0, v[18:19]
	s_mov_b64 s[8:9], 0x3500400
	s_ashr_i32 s19, s18, 31
	v_lshl_add_u64 v[22:23], v[4:5], 0, s[8:9]
	s_lshl_b64 s[8:9], s[18:19], 11
	s_lshl_b64 s[12:13], s[6:7], 2
	s_add_u32 s10, s10, s12
	s_addc_u32 s11, s11, s13
	s_add_u32 s10, s10, 0xb6000
	v_lshlrev_b32_e32 v1, 2, v1
	v_lshlrev_b32_e32 v28, 2, v3
	v_cmp_eq_u32_e64 s[0:1], 0, v2
	s_addc_u32 s11, s11, 0
	s_lshl_b64 s[14:15], s[18:19], 2
	v_lshlrev_b32_e32 v18, 4, v2
	s_mov_b64 s[26:27], 0x11000
	s_mov_b32 s12, 0x11000
	s_movk_i32 s13, 0x7fff
	s_mov_b32 s22, 0xffff0000
	s_cmpk_lg_i32 s18, 0x800
	s_cbranch_scc1 .LBB0_115
	v_lshrrev_b32_e32 v112, 1, v18
	s_lshl_b64 s[12:13], s[6:7], 12
	s_add_u32 s14, s16, s12
	s_addc_u32 s15, s17, s13
	s_add_u32 s36, s20, s12
	s_addc_u32 s37, s21, s13
	s_lshl_b64 s[12:13], s[6:7], 11
	s_add_u32 s8, s34, s12
	s_addc_u32 s9, s35, s13
	s_add_u32 s8, s8, 0x3500000
	s_addc_u32 s9, s9, 0
	s_add_u32 s26, s34, 0x11000
	s_addc_u32 s27, s35, 0
	global_load_dwordx4 v[32:35], v[20:21], off
	global_load_dwordx4 v[36:39], v[20:21], off offset:1024
	global_load_dwordx4 v[40:43], v[20:21], off offset:2048
	global_load_dwordx4 v[44:47], v[20:21], off offset:3072
	global_load_dwordx4 v[48:51], v18, s[14:15] nt
	global_load_dwordx4 v[52:55], v18, s[14:15] offset:1024 nt
	global_load_dwordx4 v[56:59], v18, s[14:15] offset:2048 nt
	global_load_dwordx4 v[60:63], v18, s[14:15] offset:3072 nt
	global_load_dwordx4 v[80:83], v18, s[26:27]
	global_load_dwordx4 v[84:87], v18, s[26:27] offset:1024
	global_load_dwordx4 v[88:91], v18, s[26:27] offset:2048
	global_load_dwordx4 v[92:95], v18, s[26:27] offset:3072
	s_add_u32 s14, s14, 0x800000
	s_addc_u32 s15, s15, 0
	s_add_u32 s26, s26, 0x6000
	s_addc_u32 s27, s27, 0
	global_load_dwordx4 v[64:67], v18, s[14:15] nt
	global_load_dwordx4 v[68:71], v18, s[14:15] offset:1024 nt
	global_load_dwordx4 v[72:75], v18, s[14:15] offset:2048 nt
	global_load_dwordx4 v[76:79], v18, s[14:15] offset:3072 nt
	global_load_dwordx4 v[96:99], v18, s[26:27]
	global_load_dwordx4 v[100:103], v18, s[26:27] offset:1024
	global_load_dwordx4 v[104:107], v18, s[26:27] offset:2048
	global_load_dwordx4 v[108:111], v18, s[26:27] offset:3072
	s_waitcnt vmcnt(8)
	v_mul_f32_e32 v29, v49, v49
	v_mul_f32_e32 v30, v51, v51
	v_mul_f32_e32 v31, v53, v53
	v_mul_f32_e32 v113, v55, v55
	v_mul_f32_e32 v114, v57, v57
	v_mul_f32_e32 v115, v59, v59
	v_mul_f32_e32 v116, v61, v61
	v_mul_f32_e32 v117, v63, v63
	v_fmac_f32_e32 v29, v48, v48
	v_fmac_f32_e32 v30, v50, v50
	v_fmac_f32_e32 v31, v52, v52
	v_fmac_f32_e32 v113, v54, v54
	v_fmac_f32_e32 v114, v56, v56
	v_fmac_f32_e32 v115, v58, v58
	v_fmac_f32_e32 v116, v60, v60
	v_fmac_f32_e32 v117, v62, v62
	v_add_f32_e32 v29, v29, v30
	v_add_f32_e32 v31, v31, v113
	v_add_f32_e32 v114, v114, v115
	v_add_f32_e32 v116, v116, v117
	v_add_f32_e32 v29, v29, v31
	v_add_f32_e32 v29, v29, v114
	v_add_f32_e32 v29, v29, v116
	ds_bpermute_b32 v30, v1, v29
	v_mul_f32_e32 v48, v48, v32
	v_mul_f32_e32 v49, v49, v33
	v_mul_f32_e32 v50, v50, v34
	v_mul_f32_e32 v51, v51, v35
	v_mul_f32_e32 v52, v52, v36
	v_mul_f32_e32 v53, v53, v37
	v_mul_f32_e32 v54, v54, v38
	v_mul_f32_e32 v55, v55, v39
	s_waitcnt lgkmcnt(0)
	v_add_f32_e32 v29, v29, v30
	ds_bpermute_b32 v30, v24, v29
	v_mul_f32_e32 v56, v56, v40
	v_mul_f32_e32 v57, v57, v41
	v_mul_f32_e32 v58, v58, v42
	v_mul_f32_e32 v59, v59, v43
	v_mul_f32_e32 v60, v60, v44
	v_mul_f32_e32 v61, v61, v45
	v_mul_f32_e32 v62, v62, v46
	v_mul_f32_e32 v63, v63, v47
	s_waitcnt lgkmcnt(0)
	v_add_f32_e32 v29, v29, v30
	ds_bpermute_b32 v30, v25, v29
	v_add_f32_e32 v80, 1.0, v80
	v_add_f32_e32 v81, 1.0, v81
	v_add_f32_e32 v82, 1.0, v82
	v_add_f32_e32 v83, 1.0, v83
	v_add_f32_e32 v84, 1.0, v84
	v_add_f32_e32 v85, 1.0, v85
	v_add_f32_e32 v86, 1.0, v86
	v_add_f32_e32 v87, 1.0, v87
	s_waitcnt lgkmcnt(0)
	v_add_f32_e32 v29, v29, v30
	ds_bpermute_b32 v30, v26, v29
	v_add_f32_e32 v88, 1.0, v88
	v_add_f32_e32 v89, 1.0, v89
	v_add_f32_e32 v90, 1.0, v90
	v_add_f32_e32 v91, 1.0, v91
	v_add_f32_e32 v92, 1.0, v92
	v_add_f32_e32 v93, 1.0, v93
	v_add_f32_e32 v94, 1.0, v94
	v_add_f32_e32 v95, 1.0, v95
	s_waitcnt lgkmcnt(0)
	v_add_f32_e32 v29, v29, v30
	ds_bpermute_b32 v30, v27, v29
	v_mul_f32_e32 v48, v48, v80
	v_mul_f32_e32 v49, v49, v81
	v_mul_f32_e32 v50, v50, v82
	v_mul_f32_e32 v51, v51, v83
	v_mul_f32_e32 v52, v52, v84
	v_mul_f32_e32 v53, v53, v85
	v_mul_f32_e32 v54, v54, v86
	v_mul_f32_e32 v55, v55, v87
	s_waitcnt lgkmcnt(0)
	v_add_f32_e32 v29, v29, v30
	ds_bpermute_b32 v30, v28, v29
	v_mul_f32_e32 v56, v56, v88
	v_mul_f32_e32 v57, v57, v89
	v_mul_f32_e32 v58, v58, v90
	v_mul_f32_e32 v59, v59, v91
	v_mul_f32_e32 v60, v60, v92
	v_mul_f32_e32 v61, v61, v93
	v_mul_f32_e32 v62, v62, v94
	v_mul_f32_e32 v63, v63, v95
	s_waitcnt lgkmcnt(0)
	v_add_f32_e32 v29, v29, v30
	s_mov_b64 s[22:23], exec
	s_mov_b64 exec, s[0:1]
	global_store_dword v19, v29, s[10:11]
	s_mov_b64 exec, s[22:23]
	s_add_u32 s10, s10, 0x2000
	s_addc_u32 s11, s11, 0
	v_cvt_pk_bf16_f32 v2, v48, v49
	v_cvt_pk_bf16_f32 v3, v50, v51
	v_cvt_pk_bf16_f32 v4, v52, v53
	v_cvt_pk_bf16_f32 v5, v54, v55
	v_cvt_pk_bf16_f32 v6, v56, v57
	v_cvt_pk_bf16_f32 v7, v58, v59
	v_cvt_pk_bf16_f32 v8, v60, v61
	v_cvt_pk_bf16_f32 v9, v62, v63
	global_store_dwordx2 v112, v[2:3], s[8:9]
	global_store_dwordx2 v112, v[4:5], s[8:9] offset:512
	global_store_dwordx2 v112, v[6:7], s[8:9] offset:1024
	global_store_dwordx2 v112, v[8:9], s[8:9] offset:1536
	s_add_u32 s8, s8, 0x400000
	s_addc_u32 s9, s9, 0
	s_add_u32 s14, s14, 0x800000
	s_addc_u32 s15, s15, 0
	s_add_u32 s26, s26, 0x6000
	s_addc_u32 s27, s27, 0
	global_load_dwordx4 v[48:51], v18, s[14:15] nt
	global_load_dwordx4 v[52:55], v18, s[14:15] offset:1024 nt
	global_load_dwordx4 v[56:59], v18, s[14:15] offset:2048 nt
	global_load_dwordx4 v[60:63], v18, s[14:15] offset:3072 nt
	global_load_dwordx4 v[80:83], v18, s[26:27]
	global_load_dwordx4 v[84:87], v18, s[26:27] offset:1024
	global_load_dwordx4 v[88:91], v18, s[26:27] offset:2048
	global_load_dwordx4 v[92:95], v18, s[26:27] offset:3072
	s_waitcnt vmcnt(13)
	v_mul_f32_e32 v29, v65, v65
	v_mul_f32_e32 v30, v67, v67
	v_mul_f32_e32 v31, v69, v69
	v_mul_f32_e32 v113, v71, v71
	v_mul_f32_e32 v114, v73, v73
	v_mul_f32_e32 v115, v75, v75
	v_mul_f32_e32 v116, v77, v77
	v_mul_f32_e32 v117, v79, v79
	v_fmac_f32_e32 v29, v64, v64
	v_fmac_f32_e32 v30, v66, v66
	v_fmac_f32_e32 v31, v68, v68
	v_fmac_f32_e32 v113, v70, v70
	v_fmac_f32_e32 v114, v72, v72
	v_fmac_f32_e32 v115, v74, v74
	v_fmac_f32_e32 v116, v76, v76
	v_fmac_f32_e32 v117, v78, v78
	v_add_f32_e32 v29, v29, v30
	v_add_f32_e32 v31, v31, v113
	v_add_f32_e32 v114, v114, v115
	v_add_f32_e32 v116, v116, v117
	v_add_f32_e32 v29, v29, v31
	v_add_f32_e32 v29, v29, v114
	v_add_f32_e32 v29, v29, v116
	ds_bpermute_b32 v30, v1, v29
	v_mul_f32_e32 v64, v64, v32
	v_mul_f32_e32 v65, v65, v33
	v_mul_f32_e32 v66, v66, v34
	v_mul_f32_e32 v67, v67, v35
	v_mul_f32_e32 v68, v68, v36
	v_mul_f32_e32 v69, v69, v37
	v_mul_f32_e32 v70, v70, v38
	v_mul_f32_e32 v71, v71, v39
	s_waitcnt lgkmcnt(0)
	v_add_f32_e32 v29, v29, v30
	ds_bpermute_b32 v30, v24, v29
	v_mul_f32_e32 v72, v72, v40
	v_mul_f32_e32 v73, v73, v41
	v_mul_f32_e32 v74, v74, v42
	v_mul_f32_e32 v75, v75, v43
	v_mul_f32_e32 v76, v76, v44
	v_mul_f32_e32 v77, v77, v45
	v_mul_f32_e32 v78, v78, v46
	v_mul_f32_e32 v79, v79, v47
	s_waitcnt lgkmcnt(0)
	v_add_f32_e32 v29, v29, v30
	ds_bpermute_b32 v30, v25, v29
	v_add_f32_e32 v96, 1.0, v96
	v_add_f32_e32 v97, 1.0, v97
	v_add_f32_e32 v98, 1.0, v98
	v_add_f32_e32 v99, 1.0, v99
	v_add_f32_e32 v100, 1.0, v100
	v_add_f32_e32 v101, 1.0, v101
	v_add_f32_e32 v102, 1.0, v102
	v_add_f32_e32 v103, 1.0, v103
	s_waitcnt lgkmcnt(0)
	v_add_f32_e32 v29, v29, v30
	ds_bpermute_b32 v30, v26, v29
	v_add_f32_e32 v104, 1.0, v104
	v_add_f32_e32 v105, 1.0, v105
	v_add_f32_e32 v106, 1.0, v106
	v_add_f32_e32 v107, 1.0, v107
	v_add_f32_e32 v108, 1.0, v108
	v_add_f32_e32 v109, 1.0, v109
	v_add_f32_e32 v110, 1.0, v110
	v_add_f32_e32 v111, 1.0, v111
	s_waitcnt lgkmcnt(0)
	v_add_f32_e32 v29, v29, v30
	ds_bpermute_b32 v30, v27, v29
	v_mul_f32_e32 v64, v64, v96
	v_mul_f32_e32 v65, v65, v97
	v_mul_f32_e32 v66, v66, v98
	v_mul_f32_e32 v67, v67, v99
	v_mul_f32_e32 v68, v68, v100
	v_mul_f32_e32 v69, v69, v101
	v_mul_f32_e32 v70, v70, v102
	v_mul_f32_e32 v71, v71, v103
	s_waitcnt lgkmcnt(0)
	v_add_f32_e32 v29, v29, v30
	ds_bpermute_b32 v30, v28, v29
	v_mul_f32_e32 v72, v72, v104
	v_mul_f32_e32 v73, v73, v105
	v_mul_f32_e32 v74, v74, v106
	v_mul_f32_e32 v75, v75, v107
	v_mul_f32_e32 v76, v76, v108
	v_mul_f32_e32 v77, v77, v109
	v_mul_f32_e32 v78, v78, v110
	v_mul_f32_e32 v79, v79, v111
	s_waitcnt lgkmcnt(0)
	v_add_f32_e32 v29, v29, v30
	s_mov_b64 s[22:23], exec
	s_mov_b64 exec, s[0:1]
	global_store_dword v19, v29, s[10:11]
	s_mov_b64 exec, s[22:23]
	s_add_u32 s10, s10, 0x2000
	s_addc_u32 s11, s11, 0
	v_cvt_pk_bf16_f32 v10, v64, v65
	v_cvt_pk_bf16_f32 v11, v66, v67
	v_cvt_pk_bf16_f32 v12, v68, v69
	v_cvt_pk_bf16_f32 v13, v70, v71
	v_cvt_pk_bf16_f32 v14, v72, v73
	v_cvt_pk_bf16_f32 v15, v74, v75
	v_cvt_pk_bf16_f32 v16, v76, v77
	v_cvt_pk_bf16_f32 v17, v78, v79
	global_store_dwordx2 v112, v[10:11], s[8:9]
	global_store_dwordx2 v112, v[12:13], s[8:9] offset:512
	global_store_dwordx2 v112, v[14:15], s[8:9] offset:1024
	global_store_dwordx2 v112, v[16:17], s[8:9] offset:1536
	s_add_u32 s8, s8, 0x400000
	s_addc_u32 s9, s9, 0
	s_add_u32 s14, s14, 0x800000
	s_addc_u32 s15, s15, 0
	s_add_u32 s26, s26, 0x6000
	s_addc_u32 s27, s27, 0
	global_load_dwordx4 v[64:67], v18, s[14:15] nt
	global_load_dwordx4 v[68:71], v18, s[14:15] offset:1024 nt
	global_load_dwordx4 v[72:75], v18, s[14:15] offset:2048 nt
	global_load_dwordx4 v[76:79], v18, s[14:15] offset:3072 nt
	global_load_dwordx4 v[96:99], v18, s[26:27]
	global_load_dwordx4 v[100:103], v18, s[26:27] offset:1024
	global_load_dwordx4 v[104:107], v18, s[26:27] offset:2048
	global_load_dwordx4 v[108:111], v18, s[26:27] offset:3072
	s_waitcnt vmcnt(13)
	v_mul_f32_e32 v29, v49, v49
	v_mul_f32_e32 v30, v51, v51
	v_mul_f32_e32 v31, v53, v53
	v_mul_f32_e32 v113, v55, v55
	v_mul_f32_e32 v114, v57, v57
	v_mul_f32_e32 v115, v59, v59
	v_mul_f32_e32 v116, v61, v61
	v_mul_f32_e32 v117, v63, v63
	v_fmac_f32_e32 v29, v48, v48
	v_fmac_f32_e32 v30, v50, v50
	v_fmac_f32_e32 v31, v52, v52
	v_fmac_f32_e32 v113, v54, v54
	v_fmac_f32_e32 v114, v56, v56
	v_fmac_f32_e32 v115, v58, v58
	v_fmac_f32_e32 v116, v60, v60
	v_fmac_f32_e32 v117, v62, v62
	v_add_f32_e32 v29, v29, v30
	v_add_f32_e32 v31, v31, v113
	v_add_f32_e32 v114, v114, v115
	v_add_f32_e32 v116, v116, v117
	v_add_f32_e32 v29, v29, v31
	v_add_f32_e32 v29, v29, v114
	v_add_f32_e32 v29, v29, v116
	ds_bpermute_b32 v30, v1, v29
	v_mul_f32_e32 v48, v48, v32
	v_mul_f32_e32 v49, v49, v33
	v_mul_f32_e32 v50, v50, v34
	v_mul_f32_e32 v51, v51, v35
	v_mul_f32_e32 v52, v52, v36
	v_mul_f32_e32 v53, v53, v37
	v_mul_f32_e32 v54, v54, v38
	v_mul_f32_e32 v55, v55, v39
	s_waitcnt lgkmcnt(0)
	v_add_f32_e32 v29, v29, v30
	ds_bpermute_b32 v30, v24, v29
	v_mul_f32_e32 v56, v56, v40
	v_mul_f32_e32 v57, v57, v41
	v_mul_f32_e32 v58, v58, v42
	v_mul_f32_e32 v59, v59, v43
	v_mul_f32_e32 v60, v60, v44
	v_mul_f32_e32 v61, v61, v45
	v_mul_f32_e32 v62, v62, v46
	v_mul_f32_e32 v63, v63, v47
	s_waitcnt lgkmcnt(0)
	v_add_f32_e32 v29, v29, v30
	ds_bpermute_b32 v30, v25, v29
	v_add_f32_e32 v80, 1.0, v80
	v_add_f32_e32 v81, 1.0, v81
	v_add_f32_e32 v82, 1.0, v82
	v_add_f32_e32 v83, 1.0, v83
	v_add_f32_e32 v84, 1.0, v84
	v_add_f32_e32 v85, 1.0, v85
	v_add_f32_e32 v86, 1.0, v86
	v_add_f32_e32 v87, 1.0, v87
	s_waitcnt lgkmcnt(0)
	v_add_f32_e32 v29, v29, v30
	ds_bpermute_b32 v30, v26, v29
	v_add_f32_e32 v88, 1.0, v88
	v_add_f32_e32 v89, 1.0, v89
	v_add_f32_e32 v90, 1.0, v90
	v_add_f32_e32 v91, 1.0, v91
	v_add_f32_e32 v92, 1.0, v92
	v_add_f32_e32 v93, 1.0, v93
	v_add_f32_e32 v94, 1.0, v94
	v_add_f32_e32 v95, 1.0, v95
	s_waitcnt lgkmcnt(0)
	v_add_f32_e32 v29, v29, v30
	ds_bpermute_b32 v30, v27, v29
	v_mul_f32_e32 v48, v48, v80
	v_mul_f32_e32 v49, v49, v81
	v_mul_f32_e32 v50, v50, v82
	v_mul_f32_e32 v51, v51, v83
	v_mul_f32_e32 v52, v52, v84
	v_mul_f32_e32 v53, v53, v85
	v_mul_f32_e32 v54, v54, v86
	v_mul_f32_e32 v55, v55, v87
	s_waitcnt lgkmcnt(0)
	v_add_f32_e32 v29, v29, v30
	ds_bpermute_b32 v30, v28, v29
	v_mul_f32_e32 v56, v56, v88
	v_mul_f32_e32 v57, v57, v89
	v_mul_f32_e32 v58, v58, v90
	v_mul_f32_e32 v59, v59, v91
	v_mul_f32_e32 v60, v60, v92
	v_mul_f32_e32 v61, v61, v93
	v_mul_f32_e32 v62, v62, v94
	v_mul_f32_e32 v63, v63, v95
	s_waitcnt lgkmcnt(0)
	v_add_f32_e32 v29, v29, v30
	s_mov_b64 s[22:23], exec
	s_mov_b64 exec, s[0:1]
	global_store_dword v19, v29, s[10:11]
	s_mov_b64 exec, s[22:23]
	s_add_u32 s10, s10, 0x2000
	s_addc_u32 s11, s11, 0
	v_cvt_pk_bf16_f32 v2, v48, v49
	v_cvt_pk_bf16_f32 v3, v50, v51
	v_cvt_pk_bf16_f32 v4, v52, v53
	v_cvt_pk_bf16_f32 v5, v54, v55
	v_cvt_pk_bf16_f32 v6, v56, v57
	v_cvt_pk_bf16_f32 v7, v58, v59
	v_cvt_pk_bf16_f32 v8, v60, v61
	v_cvt_pk_bf16_f32 v9, v62, v63
	global_store_dwordx2 v112, v[2:3], s[8:9]
	global_store_dwordx2 v112, v[4:5], s[8:9] offset:512
	global_store_dwordx2 v112, v[6:7], s[8:9] offset:1024
	global_store_dwordx2 v112, v[8:9], s[8:9] offset:1536
	s_add_u32 s8, s8, 0x400000
	s_addc_u32 s9, s9, 0
	s_add_u32 s14, s14, 0x800000
	s_addc_u32 s15, s15, 0
	s_add_u32 s26, s26, 0x6000
	s_addc_u32 s27, s27, 0
	global_load_dwordx4 v[48:51], v18, s[14:15] nt
	global_load_dwordx4 v[52:55], v18, s[14:15] offset:1024 nt
	global_load_dwordx4 v[56:59], v18, s[14:15] offset:2048 nt
	global_load_dwordx4 v[60:63], v18, s[14:15] offset:3072 nt
	global_load_dwordx4 v[80:83], v18, s[26:27]
	global_load_dwordx4 v[84:87], v18, s[26:27] offset:1024
	global_load_dwordx4 v[88:91], v18, s[26:27] offset:2048
	global_load_dwordx4 v[92:95], v18, s[26:27] offset:3072
	s_waitcnt vmcnt(13)
	v_mul_f32_e32 v29, v65, v65
	v_mul_f32_e32 v30, v67, v67
	v_mul_f32_e32 v31, v69, v69
	v_mul_f32_e32 v113, v71, v71
	v_mul_f32_e32 v114, v73, v73
	v_mul_f32_e32 v115, v75, v75
	v_mul_f32_e32 v116, v77, v77
	v_mul_f32_e32 v117, v79, v79
	v_fmac_f32_e32 v29, v64, v64
	v_fmac_f32_e32 v30, v66, v66
	v_fmac_f32_e32 v31, v68, v68
	v_fmac_f32_e32 v113, v70, v70
	v_fmac_f32_e32 v114, v72, v72
	v_fmac_f32_e32 v115, v74, v74
	v_fmac_f32_e32 v116, v76, v76
	v_fmac_f32_e32 v117, v78, v78
	v_add_f32_e32 v29, v29, v30
	v_add_f32_e32 v31, v31, v113
	v_add_f32_e32 v114, v114, v115
	v_add_f32_e32 v116, v116, v117
	v_add_f32_e32 v29, v29, v31
	v_add_f32_e32 v29, v29, v114
	v_add_f32_e32 v29, v29, v116
	ds_bpermute_b32 v30, v1, v29
	v_mul_f32_e32 v64, v64, v32
	v_mul_f32_e32 v65, v65, v33
	v_mul_f32_e32 v66, v66, v34
	v_mul_f32_e32 v67, v67, v35
	v_mul_f32_e32 v68, v68, v36
	v_mul_f32_e32 v69, v69, v37
	v_mul_f32_e32 v70, v70, v38
	v_mul_f32_e32 v71, v71, v39
	s_waitcnt lgkmcnt(0)
	v_add_f32_e32 v29, v29, v30
	ds_bpermute_b32 v30, v24, v29
	v_mul_f32_e32 v72, v72, v40
	v_mul_f32_e32 v73, v73, v41
	v_mul_f32_e32 v74, v74, v42
	v_mul_f32_e32 v75, v75, v43
	v_mul_f32_e32 v76, v76, v44
	v_mul_f32_e32 v77, v77, v45
	v_mul_f32_e32 v78, v78, v46
	v_mul_f32_e32 v79, v79, v47
	s_waitcnt lgkmcnt(0)
	v_add_f32_e32 v29, v29, v30
	ds_bpermute_b32 v30, v25, v29
	v_add_f32_e32 v96, 1.0, v96
	v_add_f32_e32 v97, 1.0, v97
	v_add_f32_e32 v98, 1.0, v98
	v_add_f32_e32 v99, 1.0, v99
	v_add_f32_e32 v100, 1.0, v100
	v_add_f32_e32 v101, 1.0, v101
	v_add_f32_e32 v102, 1.0, v102
	v_add_f32_e32 v103, 1.0, v103
	s_waitcnt lgkmcnt(0)
	v_add_f32_e32 v29, v29, v30
	ds_bpermute_b32 v30, v26, v29
	v_add_f32_e32 v104, 1.0, v104
	v_add_f32_e32 v105, 1.0, v105
	v_add_f32_e32 v106, 1.0, v106
	v_add_f32_e32 v107, 1.0, v107
	v_add_f32_e32 v108, 1.0, v108
	v_add_f32_e32 v109, 1.0, v109
	v_add_f32_e32 v110, 1.0, v110
	v_add_f32_e32 v111, 1.0, v111
	s_waitcnt lgkmcnt(0)
	v_add_f32_e32 v29, v29, v30
	ds_bpermute_b32 v30, v27, v29
	v_mul_f32_e32 v64, v64, v96
	v_mul_f32_e32 v65, v65, v97
	v_mul_f32_e32 v66, v66, v98
	v_mul_f32_e32 v67, v67, v99
	v_mul_f32_e32 v68, v68, v100
	v_mul_f32_e32 v69, v69, v101
	v_mul_f32_e32 v70, v70, v102
	v_mul_f32_e32 v71, v71, v103
	s_waitcnt lgkmcnt(0)
	v_add_f32_e32 v29, v29, v30
	ds_bpermute_b32 v30, v28, v29
	v_mul_f32_e32 v72, v72, v104
	v_mul_f32_e32 v73, v73, v105
	v_mul_f32_e32 v74, v74, v106
	v_mul_f32_e32 v75, v75, v107
	v_mul_f32_e32 v76, v76, v108
	v_mul_f32_e32 v77, v77, v109
	v_mul_f32_e32 v78, v78, v110
	v_mul_f32_e32 v79, v79, v111
	s_waitcnt lgkmcnt(0)
	v_add_f32_e32 v29, v29, v30
	s_mov_b64 s[22:23], exec
	s_mov_b64 exec, s[0:1]
	global_store_dword v19, v29, s[10:11]
	s_mov_b64 exec, s[22:23]
	s_add_u32 s10, s10, 0x2000
	s_addc_u32 s11, s11, 0
	v_cvt_pk_bf16_f32 v10, v64, v65
	v_cvt_pk_bf16_f32 v11, v66, v67
	v_cvt_pk_bf16_f32 v12, v68, v69
	v_cvt_pk_bf16_f32 v13, v70, v71
	v_cvt_pk_bf16_f32 v14, v72, v73
	v_cvt_pk_bf16_f32 v15, v74, v75
	v_cvt_pk_bf16_f32 v16, v76, v77
	v_cvt_pk_bf16_f32 v17, v78, v79
	global_store_dwordx2 v112, v[10:11], s[8:9]
	global_store_dwordx2 v112, v[12:13], s[8:9] offset:512
	global_store_dwordx2 v112, v[14:15], s[8:9] offset:1024
	global_store_dwordx2 v112, v[16:17], s[8:9] offset:1536
	s_add_u32 s8, s8, 0x400000
	s_addc_u32 s9, s9, 0
	s_add_u32 s14, s14, 0x800000
	s_addc_u32 s15, s15, 0
	s_add_u32 s26, s26, 0x6000
	s_addc_u32 s27, s27, 0
	global_load_dwordx4 v[64:67], v18, s[14:15] nt
	global_load_dwordx4 v[68:71], v18, s[14:15] offset:1024 nt
	global_load_dwordx4 v[72:75], v18, s[14:15] offset:2048 nt
	global_load_dwordx4 v[76:79], v18, s[14:15] offset:3072 nt
	global_load_dwordx4 v[96:99], v18, s[26:27]
	global_load_dwordx4 v[100:103], v18, s[26:27] offset:1024
	global_load_dwordx4 v[104:107], v18, s[26:27] offset:2048
	global_load_dwordx4 v[108:111], v18, s[26:27] offset:3072
	s_waitcnt vmcnt(13)
	v_mul_f32_e32 v29, v49, v49
	v_mul_f32_e32 v30, v51, v51
	v_mul_f32_e32 v31, v53, v53
	v_mul_f32_e32 v113, v55, v55
	v_mul_f32_e32 v114, v57, v57
	v_mul_f32_e32 v115, v59, v59
	v_mul_f32_e32 v116, v61, v61
	v_mul_f32_e32 v117, v63, v63
	v_fmac_f32_e32 v29, v48, v48
	v_fmac_f32_e32 v30, v50, v50
	v_fmac_f32_e32 v31, v52, v52
	v_fmac_f32_e32 v113, v54, v54
	v_fmac_f32_e32 v114, v56, v56
	v_fmac_f32_e32 v115, v58, v58
	v_fmac_f32_e32 v116, v60, v60
	v_fmac_f32_e32 v117, v62, v62
	v_add_f32_e32 v29, v29, v30
	v_add_f32_e32 v31, v31, v113
	v_add_f32_e32 v114, v114, v115
	v_add_f32_e32 v116, v116, v117
	v_add_f32_e32 v29, v29, v31
	v_add_f32_e32 v29, v29, v114
	v_add_f32_e32 v29, v29, v116
	ds_bpermute_b32 v30, v1, v29
	v_mul_f32_e32 v48, v48, v32
	v_mul_f32_e32 v49, v49, v33
	v_mul_f32_e32 v50, v50, v34
	v_mul_f32_e32 v51, v51, v35
	v_mul_f32_e32 v52, v52, v36
	v_mul_f32_e32 v53, v53, v37
	v_mul_f32_e32 v54, v54, v38
	v_mul_f32_e32 v55, v55, v39
	s_waitcnt lgkmcnt(0)
	v_add_f32_e32 v29, v29, v30
	ds_bpermute_b32 v30, v24, v29
	v_mul_f32_e32 v56, v56, v40
	v_mul_f32_e32 v57, v57, v41
	v_mul_f32_e32 v58, v58, v42
	v_mul_f32_e32 v59, v59, v43
	v_mul_f32_e32 v60, v60, v44
	v_mul_f32_e32 v61, v61, v45
	v_mul_f32_e32 v62, v62, v46
	v_mul_f32_e32 v63, v63, v47
	s_waitcnt lgkmcnt(0)
	v_add_f32_e32 v29, v29, v30
	ds_bpermute_b32 v30, v25, v29
	v_add_f32_e32 v80, 1.0, v80
	v_add_f32_e32 v81, 1.0, v81
	v_add_f32_e32 v82, 1.0, v82
	v_add_f32_e32 v83, 1.0, v83
	v_add_f32_e32 v84, 1.0, v84
	v_add_f32_e32 v85, 1.0, v85
	v_add_f32_e32 v86, 1.0, v86
	v_add_f32_e32 v87, 1.0, v87
	s_waitcnt lgkmcnt(0)
	v_add_f32_e32 v29, v29, v30
	ds_bpermute_b32 v30, v26, v29
	v_add_f32_e32 v88, 1.0, v88
	v_add_f32_e32 v89, 1.0, v89
	v_add_f32_e32 v90, 1.0, v90
	v_add_f32_e32 v91, 1.0, v91
	v_add_f32_e32 v92, 1.0, v92
	v_add_f32_e32 v93, 1.0, v93
	v_add_f32_e32 v94, 1.0, v94
	v_add_f32_e32 v95, 1.0, v95
	s_waitcnt lgkmcnt(0)
	v_add_f32_e32 v29, v29, v30
	ds_bpermute_b32 v30, v27, v29
	v_mul_f32_e32 v48, v48, v80
	v_mul_f32_e32 v49, v49, v81
	v_mul_f32_e32 v50, v50, v82
	v_mul_f32_e32 v51, v51, v83
	v_mul_f32_e32 v52, v52, v84
	v_mul_f32_e32 v53, v53, v85
	v_mul_f32_e32 v54, v54, v86
	v_mul_f32_e32 v55, v55, v87
	s_waitcnt lgkmcnt(0)
	v_add_f32_e32 v29, v29, v30
	ds_bpermute_b32 v30, v28, v29
	v_mul_f32_e32 v56, v56, v88
	v_mul_f32_e32 v57, v57, v89
	v_mul_f32_e32 v58, v58, v90
	v_mul_f32_e32 v59, v59, v91
	v_mul_f32_e32 v60, v60, v92
	v_mul_f32_e32 v61, v61, v93
	v_mul_f32_e32 v62, v62, v94
	v_mul_f32_e32 v63, v63, v95
	s_waitcnt lgkmcnt(0)
	v_add_f32_e32 v29, v29, v30
	s_mov_b64 s[22:23], exec
	s_mov_b64 exec, s[0:1]
	global_store_dword v19, v29, s[10:11]
	s_mov_b64 exec, s[22:23]
	s_add_u32 s10, s10, 0x2000
	s_addc_u32 s11, s11, 0
	v_cvt_pk_bf16_f32 v2, v48, v49
	v_cvt_pk_bf16_f32 v3, v50, v51
	v_cvt_pk_bf16_f32 v4, v52, v53
	v_cvt_pk_bf16_f32 v5, v54, v55
	v_cvt_pk_bf16_f32 v6, v56, v57
	v_cvt_pk_bf16_f32 v7, v58, v59
	v_cvt_pk_bf16_f32 v8, v60, v61
	v_cvt_pk_bf16_f32 v9, v62, v63
	global_store_dwordx2 v112, v[2:3], s[8:9]
	global_store_dwordx2 v112, v[4:5], s[8:9] offset:512
	global_store_dwordx2 v112, v[6:7], s[8:9] offset:1024
	global_store_dwordx2 v112, v[8:9], s[8:9] offset:1536
	s_add_u32 s8, s8, 0x400000
	s_addc_u32 s9, s9, 0
	s_add_u32 s14, s14, 0x800000
	s_addc_u32 s15, s15, 0
	s_add_u32 s26, s26, 0x6000
	s_addc_u32 s27, s27, 0
	global_load_dwordx4 v[48:51], v18, s[14:15] nt
	global_load_dwordx4 v[52:55], v18, s[14:15] offset:1024 nt
	global_load_dwordx4 v[56:59], v18, s[14:15] offset:2048 nt
	global_load_dwordx4 v[60:63], v18, s[14:15] offset:3072 nt
	global_load_dwordx4 v[80:83], v18, s[26:27]
	global_load_dwordx4 v[84:87], v18, s[26:27] offset:1024
	global_load_dwordx4 v[88:91], v18, s[26:27] offset:2048
	global_load_dwordx4 v[92:95], v18, s[26:27] offset:3072
	s_waitcnt vmcnt(13)
	v_mul_f32_e32 v29, v65, v65
	v_mul_f32_e32 v30, v67, v67
	v_mul_f32_e32 v31, v69, v69
	v_mul_f32_e32 v113, v71, v71
	v_mul_f32_e32 v114, v73, v73
	v_mul_f32_e32 v115, v75, v75
	v_mul_f32_e32 v116, v77, v77
	v_mul_f32_e32 v117, v79, v79
	v_fmac_f32_e32 v29, v64, v64
	v_fmac_f32_e32 v30, v66, v66
	v_fmac_f32_e32 v31, v68, v68
	v_fmac_f32_e32 v113, v70, v70
	v_fmac_f32_e32 v114, v72, v72
	v_fmac_f32_e32 v115, v74, v74
	v_fmac_f32_e32 v116, v76, v76
	v_fmac_f32_e32 v117, v78, v78
	v_add_f32_e32 v29, v29, v30
	v_add_f32_e32 v31, v31, v113
	v_add_f32_e32 v114, v114, v115
	v_add_f32_e32 v116, v116, v117
	v_add_f32_e32 v29, v29, v31
	v_add_f32_e32 v29, v29, v114
	v_add_f32_e32 v29, v29, v116
	ds_bpermute_b32 v30, v1, v29
	v_mul_f32_e32 v64, v64, v32
	v_mul_f32_e32 v65, v65, v33
	v_mul_f32_e32 v66, v66, v34
	v_mul_f32_e32 v67, v67, v35
	v_mul_f32_e32 v68, v68, v36
	v_mul_f32_e32 v69, v69, v37
	v_mul_f32_e32 v70, v70, v38
	v_mul_f32_e32 v71, v71, v39
	s_waitcnt lgkmcnt(0)
	v_add_f32_e32 v29, v29, v30
	ds_bpermute_b32 v30, v24, v29
	v_mul_f32_e32 v72, v72, v40
	v_mul_f32_e32 v73, v73, v41
	v_mul_f32_e32 v74, v74, v42
	v_mul_f32_e32 v75, v75, v43
	v_mul_f32_e32 v76, v76, v44
	v_mul_f32_e32 v77, v77, v45
	v_mul_f32_e32 v78, v78, v46
	v_mul_f32_e32 v79, v79, v47
	s_waitcnt lgkmcnt(0)
	v_add_f32_e32 v29, v29, v30
	ds_bpermute_b32 v30, v25, v29
	v_add_f32_e32 v96, 1.0, v96
	v_add_f32_e32 v97, 1.0, v97
	v_add_f32_e32 v98, 1.0, v98
	v_add_f32_e32 v99, 1.0, v99
	v_add_f32_e32 v100, 1.0, v100
	v_add_f32_e32 v101, 1.0, v101
	v_add_f32_e32 v102, 1.0, v102
	v_add_f32_e32 v103, 1.0, v103
	s_waitcnt lgkmcnt(0)
	v_add_f32_e32 v29, v29, v30
	ds_bpermute_b32 v30, v26, v29
	v_add_f32_e32 v104, 1.0, v104
	v_add_f32_e32 v105, 1.0, v105
	v_add_f32_e32 v106, 1.0, v106
	v_add_f32_e32 v107, 1.0, v107
	v_add_f32_e32 v108, 1.0, v108
	v_add_f32_e32 v109, 1.0, v109
	v_add_f32_e32 v110, 1.0, v110
	v_add_f32_e32 v111, 1.0, v111
	s_waitcnt lgkmcnt(0)
	v_add_f32_e32 v29, v29, v30
	ds_bpermute_b32 v30, v27, v29
	v_mul_f32_e32 v64, v64, v96
	v_mul_f32_e32 v65, v65, v97
	v_mul_f32_e32 v66, v66, v98
	v_mul_f32_e32 v67, v67, v99
	v_mul_f32_e32 v68, v68, v100
	v_mul_f32_e32 v69, v69, v101
	v_mul_f32_e32 v70, v70, v102
	v_mul_f32_e32 v71, v71, v103
	s_waitcnt lgkmcnt(0)
	v_add_f32_e32 v29, v29, v30
	ds_bpermute_b32 v30, v28, v29
	v_mul_f32_e32 v72, v72, v104
	v_mul_f32_e32 v73, v73, v105
	v_mul_f32_e32 v74, v74, v106
	v_mul_f32_e32 v75, v75, v107
	v_mul_f32_e32 v76, v76, v108
	v_mul_f32_e32 v77, v77, v109
	v_mul_f32_e32 v78, v78, v110
	v_mul_f32_e32 v79, v79, v111
	s_waitcnt lgkmcnt(0)
	v_add_f32_e32 v29, v29, v30
	s_mov_b64 s[22:23], exec
	s_mov_b64 exec, s[0:1]
	global_store_dword v19, v29, s[10:11]
	s_mov_b64 exec, s[22:23]
	s_add_u32 s10, s10, 0x2000
	s_addc_u32 s11, s11, 0
	v_cvt_pk_bf16_f32 v10, v64, v65
	v_cvt_pk_bf16_f32 v11, v66, v67
	v_cvt_pk_bf16_f32 v12, v68, v69
	v_cvt_pk_bf16_f32 v13, v70, v71
	v_cvt_pk_bf16_f32 v14, v72, v73
	v_cvt_pk_bf16_f32 v15, v74, v75
	v_cvt_pk_bf16_f32 v16, v76, v77
	v_cvt_pk_bf16_f32 v17, v78, v79
	global_store_dwordx2 v112, v[10:11], s[8:9]
	global_store_dwordx2 v112, v[12:13], s[8:9] offset:512
	global_store_dwordx2 v112, v[14:15], s[8:9] offset:1024
	global_store_dwordx2 v112, v[16:17], s[8:9] offset:1536
	s_add_u32 s8, s8, 0x400000
	s_addc_u32 s9, s9, 0
	s_add_u32 s14, s14, 0x800000
	s_addc_u32 s15, s15, 0
	s_add_u32 s26, s26, 0x6000
	s_addc_u32 s27, s27, 0
	global_load_dwordx4 v[64:67], v18, s[14:15] nt
	global_load_dwordx4 v[68:71], v18, s[14:15] offset:1024 nt
	global_load_dwordx4 v[72:75], v18, s[14:15] offset:2048 nt
	global_load_dwordx4 v[76:79], v18, s[14:15] offset:3072 nt
	global_load_dwordx4 v[96:99], v18, s[26:27]
	global_load_dwordx4 v[100:103], v18, s[26:27] offset:1024
	global_load_dwordx4 v[104:107], v18, s[26:27] offset:2048
	global_load_dwordx4 v[108:111], v18, s[26:27] offset:3072
	s_waitcnt vmcnt(13)
	v_mul_f32_e32 v29, v49, v49
	v_mul_f32_e32 v30, v51, v51
	v_mul_f32_e32 v31, v53, v53
	v_mul_f32_e32 v113, v55, v55
	v_mul_f32_e32 v114, v57, v57
	v_mul_f32_e32 v115, v59, v59
	v_mul_f32_e32 v116, v61, v61
	v_mul_f32_e32 v117, v63, v63
	v_fmac_f32_e32 v29, v48, v48
	v_fmac_f32_e32 v30, v50, v50
	v_fmac_f32_e32 v31, v52, v52
	v_fmac_f32_e32 v113, v54, v54
	v_fmac_f32_e32 v114, v56, v56
	v_fmac_f32_e32 v115, v58, v58
	v_fmac_f32_e32 v116, v60, v60
	v_fmac_f32_e32 v117, v62, v62
	v_add_f32_e32 v29, v29, v30
	v_add_f32_e32 v31, v31, v113
	v_add_f32_e32 v114, v114, v115
	v_add_f32_e32 v116, v116, v117
	v_add_f32_e32 v29, v29, v31
	v_add_f32_e32 v29, v29, v114
	v_add_f32_e32 v29, v29, v116
	ds_bpermute_b32 v30, v1, v29
	v_mul_f32_e32 v48, v48, v32
	v_mul_f32_e32 v49, v49, v33
	v_mul_f32_e32 v50, v50, v34
	v_mul_f32_e32 v51, v51, v35
	v_mul_f32_e32 v52, v52, v36
	v_mul_f32_e32 v53, v53, v37
	v_mul_f32_e32 v54, v54, v38
	v_mul_f32_e32 v55, v55, v39
	s_waitcnt lgkmcnt(0)
	v_add_f32_e32 v29, v29, v30
	ds_bpermute_b32 v30, v24, v29
	v_mul_f32_e32 v56, v56, v40
	v_mul_f32_e32 v57, v57, v41
	v_mul_f32_e32 v58, v58, v42
	v_mul_f32_e32 v59, v59, v43
	v_mul_f32_e32 v60, v60, v44
	v_mul_f32_e32 v61, v61, v45
	v_mul_f32_e32 v62, v62, v46
	v_mul_f32_e32 v63, v63, v47
	s_waitcnt lgkmcnt(0)
	v_add_f32_e32 v29, v29, v30
	ds_bpermute_b32 v30, v25, v29
	v_add_f32_e32 v80, 1.0, v80
	v_add_f32_e32 v81, 1.0, v81
	v_add_f32_e32 v82, 1.0, v82
	v_add_f32_e32 v83, 1.0, v83
	v_add_f32_e32 v84, 1.0, v84
	v_add_f32_e32 v85, 1.0, v85
	v_add_f32_e32 v86, 1.0, v86
	v_add_f32_e32 v87, 1.0, v87
	s_waitcnt lgkmcnt(0)
	v_add_f32_e32 v29, v29, v30
	ds_bpermute_b32 v30, v26, v29
	v_add_f32_e32 v88, 1.0, v88
	v_add_f32_e32 v89, 1.0, v89
	v_add_f32_e32 v90, 1.0, v90
	v_add_f32_e32 v91, 1.0, v91
	v_add_f32_e32 v92, 1.0, v92
	v_add_f32_e32 v93, 1.0, v93
	v_add_f32_e32 v94, 1.0, v94
	v_add_f32_e32 v95, 1.0, v95
	s_waitcnt lgkmcnt(0)
	v_add_f32_e32 v29, v29, v30
	ds_bpermute_b32 v30, v27, v29
	v_mul_f32_e32 v48, v48, v80
	v_mul_f32_e32 v49, v49, v81
	v_mul_f32_e32 v50, v50, v82
	v_mul_f32_e32 v51, v51, v83
	v_mul_f32_e32 v52, v52, v84
	v_mul_f32_e32 v53, v53, v85
	v_mul_f32_e32 v54, v54, v86
	v_mul_f32_e32 v55, v55, v87
	s_waitcnt lgkmcnt(0)
	v_add_f32_e32 v29, v29, v30
	ds_bpermute_b32 v30, v28, v29
	v_mul_f32_e32 v56, v56, v88
	v_mul_f32_e32 v57, v57, v89
	v_mul_f32_e32 v58, v58, v90
	v_mul_f32_e32 v59, v59, v91
	v_mul_f32_e32 v60, v60, v92
	v_mul_f32_e32 v61, v61, v93
	v_mul_f32_e32 v62, v62, v94
	v_mul_f32_e32 v63, v63, v95
	s_waitcnt lgkmcnt(0)
	v_add_f32_e32 v29, v29, v30
	s_mov_b64 s[22:23], exec
	s_mov_b64 exec, s[0:1]
	global_store_dword v19, v29, s[10:11]
	s_mov_b64 exec, s[22:23]
	s_add_u32 s10, s10, 0x2000
	s_addc_u32 s11, s11, 0
	v_cvt_pk_bf16_f32 v2, v48, v49
	v_cvt_pk_bf16_f32 v3, v50, v51
	v_cvt_pk_bf16_f32 v4, v52, v53
	v_cvt_pk_bf16_f32 v5, v54, v55
	v_cvt_pk_bf16_f32 v6, v56, v57
	v_cvt_pk_bf16_f32 v7, v58, v59
	v_cvt_pk_bf16_f32 v8, v60, v61
	v_cvt_pk_bf16_f32 v9, v62, v63
	global_store_dwordx2 v112, v[2:3], s[8:9]
	global_store_dwordx2 v112, v[4:5], s[8:9] offset:512
	global_store_dwordx2 v112, v[6:7], s[8:9] offset:1024
	global_store_dwordx2 v112, v[8:9], s[8:9] offset:1536
	s_add_u32 s8, s8, 0x400000
	s_addc_u32 s9, s9, 0
	s_add_u32 s26, s26, 0x6000
	s_addc_u32 s27, s27, 0
	global_load_dwordx4 v[48:51], v18, s[36:37] nt
	global_load_dwordx4 v[52:55], v18, s[36:37] offset:1024 nt
	global_load_dwordx4 v[56:59], v18, s[36:37] offset:2048 nt
	global_load_dwordx4 v[60:63], v18, s[36:37] offset:3072 nt
	global_load_dwordx4 v[80:83], v18, s[26:27]
	global_load_dwordx4 v[84:87], v18, s[26:27] offset:1024
	global_load_dwordx4 v[88:91], v18, s[26:27] offset:2048
	global_load_dwordx4 v[92:95], v18, s[26:27] offset:3072
	s_waitcnt vmcnt(13)
	v_mul_f32_e32 v29, v65, v65
	v_mul_f32_e32 v30, v67, v67
	v_mul_f32_e32 v31, v69, v69
	v_mul_f32_e32 v113, v71, v71
	v_mul_f32_e32 v114, v73, v73
	v_mul_f32_e32 v115, v75, v75
	v_mul_f32_e32 v116, v77, v77
	v_mul_f32_e32 v117, v79, v79
	v_fmac_f32_e32 v29, v64, v64
	v_fmac_f32_e32 v30, v66, v66
	v_fmac_f32_e32 v31, v68, v68
	v_fmac_f32_e32 v113, v70, v70
	v_fmac_f32_e32 v114, v72, v72
	v_fmac_f32_e32 v115, v74, v74
	v_fmac_f32_e32 v116, v76, v76
	v_fmac_f32_e32 v117, v78, v78
	v_add_f32_e32 v29, v29, v30
	v_add_f32_e32 v31, v31, v113
	v_add_f32_e32 v114, v114, v115
	v_add_f32_e32 v116, v116, v117
	v_add_f32_e32 v29, v29, v31
	v_add_f32_e32 v29, v29, v114
	v_add_f32_e32 v29, v29, v116
	ds_bpermute_b32 v30, v1, v29
	v_mul_f32_e32 v64, v64, v32
	v_mul_f32_e32 v65, v65, v33
	v_mul_f32_e32 v66, v66, v34
	v_mul_f32_e32 v67, v67, v35
	v_mul_f32_e32 v68, v68, v36
	v_mul_f32_e32 v69, v69, v37
	v_mul_f32_e32 v70, v70, v38
	v_mul_f32_e32 v71, v71, v39
	s_waitcnt lgkmcnt(0)
	v_add_f32_e32 v29, v29, v30
	ds_bpermute_b32 v30, v24, v29
	v_mul_f32_e32 v72, v72, v40
	v_mul_f32_e32 v73, v73, v41
	v_mul_f32_e32 v74, v74, v42
	v_mul_f32_e32 v75, v75, v43
	v_mul_f32_e32 v76, v76, v44
	v_mul_f32_e32 v77, v77, v45
	v_mul_f32_e32 v78, v78, v46
	v_mul_f32_e32 v79, v79, v47
	s_waitcnt lgkmcnt(0)
	v_add_f32_e32 v29, v29, v30
	ds_bpermute_b32 v30, v25, v29
	v_add_f32_e32 v96, 1.0, v96
	v_add_f32_e32 v97, 1.0, v97
	v_add_f32_e32 v98, 1.0, v98
	v_add_f32_e32 v99, 1.0, v99
	v_add_f32_e32 v100, 1.0, v100
	v_add_f32_e32 v101, 1.0, v101
	v_add_f32_e32 v102, 1.0, v102
	v_add_f32_e32 v103, 1.0, v103
	s_waitcnt lgkmcnt(0)
	v_add_f32_e32 v29, v29, v30
	ds_bpermute_b32 v30, v26, v29
	v_add_f32_e32 v104, 1.0, v104
	v_add_f32_e32 v105, 1.0, v105
	v_add_f32_e32 v106, 1.0, v106
	v_add_f32_e32 v107, 1.0, v107
	v_add_f32_e32 v108, 1.0, v108
	v_add_f32_e32 v109, 1.0, v109
	v_add_f32_e32 v110, 1.0, v110
	v_add_f32_e32 v111, 1.0, v111
	s_waitcnt lgkmcnt(0)
	v_add_f32_e32 v29, v29, v30
	ds_bpermute_b32 v30, v27, v29
	v_mul_f32_e32 v64, v64, v96
	v_mul_f32_e32 v65, v65, v97
	v_mul_f32_e32 v66, v66, v98
	v_mul_f32_e32 v67, v67, v99
	v_mul_f32_e32 v68, v68, v100
	v_mul_f32_e32 v69, v69, v101
	v_mul_f32_e32 v70, v70, v102
	v_mul_f32_e32 v71, v71, v103
	s_waitcnt lgkmcnt(0)
	v_add_f32_e32 v29, v29, v30
	ds_bpermute_b32 v30, v28, v29
	v_mul_f32_e32 v72, v72, v104
	v_mul_f32_e32 v73, v73, v105
	v_mul_f32_e32 v74, v74, v106
	v_mul_f32_e32 v75, v75, v107
	v_mul_f32_e32 v76, v76, v108
	v_mul_f32_e32 v77, v77, v109
	v_mul_f32_e32 v78, v78, v110
	v_mul_f32_e32 v79, v79, v111
	s_waitcnt lgkmcnt(0)
	v_add_f32_e32 v29, v29, v30
	s_mov_b64 s[22:23], exec
	s_mov_b64 exec, s[0:1]
	global_store_dword v19, v29, s[10:11]
	s_mov_b64 exec, s[22:23]
	s_add_u32 s10, s10, 0x2000
	s_addc_u32 s11, s11, 0
	v_cvt_pk_bf16_f32 v10, v64, v65
	v_cvt_pk_bf16_f32 v11, v66, v67
	v_cvt_pk_bf16_f32 v12, v68, v69
	v_cvt_pk_bf16_f32 v13, v70, v71
	v_cvt_pk_bf16_f32 v14, v72, v73
	v_cvt_pk_bf16_f32 v15, v74, v75
	v_cvt_pk_bf16_f32 v16, v76, v77
	v_cvt_pk_bf16_f32 v17, v78, v79
	global_store_dwordx2 v112, v[10:11], s[8:9]
	global_store_dwordx2 v112, v[12:13], s[8:9] offset:512
	global_store_dwordx2 v112, v[14:15], s[8:9] offset:1024
	global_store_dwordx2 v112, v[16:17], s[8:9] offset:1536
	s_add_u32 s8, s8, 0x400000
	s_addc_u32 s9, s9, 0
	s_waitcnt vmcnt(5)
	v_mul_f32_e32 v29, v49, v49
	v_mul_f32_e32 v30, v51, v51
	v_mul_f32_e32 v31, v53, v53
	v_mul_f32_e32 v113, v55, v55
	v_mul_f32_e32 v114, v57, v57
	v_mul_f32_e32 v115, v59, v59
	v_mul_f32_e32 v116, v61, v61
	v_mul_f32_e32 v117, v63, v63
	v_fmac_f32_e32 v29, v48, v48
	v_fmac_f32_e32 v30, v50, v50
	v_fmac_f32_e32 v31, v52, v52
	v_fmac_f32_e32 v113, v54, v54
	v_fmac_f32_e32 v114, v56, v56
	v_fmac_f32_e32 v115, v58, v58
	v_fmac_f32_e32 v116, v60, v60
	v_fmac_f32_e32 v117, v62, v62
	v_add_f32_e32 v29, v29, v30
	v_add_f32_e32 v31, v31, v113
	v_add_f32_e32 v114, v114, v115
	v_add_f32_e32 v116, v116, v117
	v_add_f32_e32 v29, v29, v31
	v_add_f32_e32 v29, v29, v114
	v_add_f32_e32 v29, v29, v116
	ds_bpermute_b32 v30, v1, v29
	v_mul_f32_e32 v48, v48, v32
	v_mul_f32_e32 v49, v49, v33
	v_mul_f32_e32 v50, v50, v34
	v_mul_f32_e32 v51, v51, v35
	v_mul_f32_e32 v52, v52, v36
	v_mul_f32_e32 v53, v53, v37
	v_mul_f32_e32 v54, v54, v38
	v_mul_f32_e32 v55, v55, v39
	s_waitcnt lgkmcnt(0)
	v_add_f32_e32 v29, v29, v30
	ds_bpermute_b32 v30, v24, v29
	v_mul_f32_e32 v56, v56, v40
	v_mul_f32_e32 v57, v57, v41
	v_mul_f32_e32 v58, v58, v42
	v_mul_f32_e32 v59, v59, v43
	v_mul_f32_e32 v60, v60, v44
	v_mul_f32_e32 v61, v61, v45
	v_mul_f32_e32 v62, v62, v46
	v_mul_f32_e32 v63, v63, v47
	s_waitcnt lgkmcnt(0)
	v_add_f32_e32 v29, v29, v30
	ds_bpermute_b32 v30, v25, v29
	v_add_f32_e32 v80, 1.0, v80
	v_add_f32_e32 v81, 1.0, v81
	v_add_f32_e32 v82, 1.0, v82
	v_add_f32_e32 v83, 1.0, v83
	v_add_f32_e32 v84, 1.0, v84
	v_add_f32_e32 v85, 1.0, v85
	v_add_f32_e32 v86, 1.0, v86
	v_add_f32_e32 v87, 1.0, v87
	s_waitcnt lgkmcnt(0)
	v_add_f32_e32 v29, v29, v30
	ds_bpermute_b32 v30, v26, v29
	v_add_f32_e32 v88, 1.0, v88
	v_add_f32_e32 v89, 1.0, v89
	v_add_f32_e32 v90, 1.0, v90
	v_add_f32_e32 v91, 1.0, v91
	v_add_f32_e32 v92, 1.0, v92
	v_add_f32_e32 v93, 1.0, v93
	v_add_f32_e32 v94, 1.0, v94
	v_add_f32_e32 v95, 1.0, v95
	s_waitcnt lgkmcnt(0)
	v_add_f32_e32 v29, v29, v30
	ds_bpermute_b32 v30, v27, v29
	v_mul_f32_e32 v48, v48, v80
	v_mul_f32_e32 v49, v49, v81
	v_mul_f32_e32 v50, v50, v82
	v_mul_f32_e32 v51, v51, v83
	v_mul_f32_e32 v52, v52, v84
	v_mul_f32_e32 v53, v53, v85
	v_mul_f32_e32 v54, v54, v86
	v_mul_f32_e32 v55, v55, v87
	s_waitcnt lgkmcnt(0)
	v_add_f32_e32 v29, v29, v30
	ds_bpermute_b32 v30, v28, v29
	v_mul_f32_e32 v56, v56, v88
	v_mul_f32_e32 v57, v57, v89
	v_mul_f32_e32 v58, v58, v90
	v_mul_f32_e32 v59, v59, v91
	v_mul_f32_e32 v60, v60, v92
	v_mul_f32_e32 v61, v61, v93
	v_mul_f32_e32 v62, v62, v94
	v_mul_f32_e32 v63, v63, v95
	s_waitcnt lgkmcnt(0)
	v_add_f32_e32 v29, v29, v30
	s_mov_b64 s[22:23], exec
	s_mov_b64 exec, s[0:1]
	global_store_dword v19, v29, s[10:11]
	s_mov_b64 exec, s[22:23]
	s_add_u32 s10, s10, 0x2000
	s_addc_u32 s11, s11, 0
	v_cvt_pk_bf16_f32 v2, v48, v49
	v_cvt_pk_bf16_f32 v3, v50, v51
	v_cvt_pk_bf16_f32 v4, v52, v53
	v_cvt_pk_bf16_f32 v5, v54, v55
	v_cvt_pk_bf16_f32 v6, v56, v57
	v_cvt_pk_bf16_f32 v7, v58, v59
	v_cvt_pk_bf16_f32 v8, v60, v61
	v_cvt_pk_bf16_f32 v9, v62, v63
	global_store_dwordx2 v112, v[2:3], s[8:9]
	global_store_dwordx2 v112, v[4:5], s[8:9] offset:512
	global_store_dwordx2 v112, v[6:7], s[8:9] offset:1024
	global_store_dwordx2 v112, v[8:9], s[8:9] offset:1536
	s_branch .LBB0_117

.LBB0_373:
	s_cmpk_lt_i32 s4, 0x4000
	s_waitcnt vmcnt(5)
	v_lshl_add_u64 v[18:19], v[84:85], 0, s[76:77]
	s_cselect_b64 s[8:9], -1, 0
	global_load_dwordx4 v[18:21], v[18:19], off
	s_and_b64 s[8:9], s[8:9], exec
	s_cselect_b32 s3, s22, 0xff
	s_and_b32 s3, s3, s4
	s_add_i32 s10, s3, 0x100
	s_cmpk_lt_i32 s4, 0x4000
	s_cselect_b64 s[8:9], -1, 0
	s_and_b64 s[8:9], s[8:9], exec
	s_cselect_b32 s13, s10, s3
	s_add_i32 s8, s4, 0xffffc000
	s_ashr_i32 s3, s4, 11
	s_lshr_b32 s10, s8, 8
	s_cmpk_lt_i32 s4, 0x4000
	s_cselect_b64 vcc, -1, 0
	s_and_b64 s[8:9], vcc, exec
	s_cselect_b32 s37, s3, s10
	s_add_i32 s12, s18, s4
	s_min_i32 s3, s12, 0x47ff
	s_mul_hi_i32 s9, s3, 0xc00
	s_mulk_i32 s3, 0xc00
	s_min_i32 s10, s12, 0x4000
	s_add_u32 s8, s14, s3
	s_addc_u32 s9, s15, s9
	s_lshl_b32 s3, s10, 7
	s_add_i32 s82, s5, s4
	s_and_b32 s70, s3, 0x3ff80
	s_min_i32 s3, s82, 0x47ff
	s_mul_hi_i32 s11, s3, 0xc00
	s_mulk_i32 s3, 0xc00
	s_min_i32 s24, s82, 0x4000
	s_add_u32 s10, s14, s3
	s_addc_u32 s11, s15, s11
	s_lshl_b32 s3, s24, 7
	s_waitcnt vmcnt(4)
	v_lshl_add_u64 v[22:23], v[72:73], 0, s[70:71]
	s_waitcnt lgkmcnt(5)
	v_lshl_add_u64 v[24:25], v[74:75], 0, s[70:71]
	s_and_b32 s70, s3, 0x3ff80
	s_min_i32 s3, s4, 0x4000
	s_lshl_b32 s3, s3, 7
	s_waitcnt vmcnt(2)
	v_lshl_add_u64 v[30:31], v[72:73], 0, s[70:71]
	v_lshl_add_u64 v[32:33], v[74:75], 0, s[70:71]
	s_and_b32 s70, s3, 0x3ff80
	v_lshl_add_u64 v[26:27], v[74:75], 0, s[70:71]
	global_load_dwordx4 v[90:93], v[26:27], off offset:16
	global_load_dwordx4 v[96:99], v[26:27], off
	v_lshl_add_u64 v[26:27], v[72:73], 0, s[70:71]
	global_load_dwordx4 v[100:103], v[26:27], off offset:16
	global_load_dwordx4 v[104:107], v[26:27], off
	v_lshl_add_u64 v[26:27], v[78:79], 0, s[76:77]
	s_waitcnt lgkmcnt(4)
	global_load_dwordx4 v[66:69], v[26:27], off
	s_waitcnt lgkmcnt(0)
	global_load_dwordx4 v[50:53], v[22:23], off offset:16
	global_load_dwordx4 v[46:49], v[22:23], off
	global_load_dwordx4 v[58:61], v[24:25], off offset:16
	global_load_dwordx4 v[54:57], v[24:25], off
	s_mul_hi_i32 s3, s37, 0x900
	s_mulk_i32 s37, 0x900
	s_waitcnt vmcnt(9)
	v_lshlrev_b32_e32 v108, 16, v18
	v_and_b32_e32 v110, 0xffff0000, v18
	v_lshlrev_b32_e32 v109, 16, v19
	v_and_b32_e32 v111, 0xffff0000, v19
	v_lshlrev_b32_e32 v112, 16, v20
	v_and_b32_e32 v114, 0xffff0000, v20
	v_lshlrev_b32_e32 v113, 16, v21
	v_and_b32_e32 v115, 0xffff0000, v21
	v_pk_mul_f32 v[18:19], v[108:109], v[108:109]
	v_pk_mul_f32 v[20:21], v[110:111], v[110:111]
	v_mov_b32_e32 v22, v114
	v_add_f32_e32 v18, v18, v20
	v_mov_b32_e32 v23, v112
	v_add_f32_e32 v18, v19, v18
	v_pk_mul_f32 v[22:23], v[22:23], v[22:23]
	v_add_f32_e32 v18, v21, v18
	v_mov_b32_e32 v24, v115
	v_mov_b32_e32 v25, v113
	v_add_f32_e32 v18, v23, v18
	v_pk_mul_f32 v[24:25], v[24:25], v[24:25]
	v_add_f32_e32 v18, v22, v18
	v_add_f32_e32 v18, v25, v18
	v_add_f32_e32 v22, v24, v18
	ds_bpermute_b32 v23, v1, v22
	global_load_dwordx4 v[62:65], v122, s[8:9]
	global_load_dwordx4 v[38:41], v122, s[10:11]
	global_load_dwordx4 v[42:45], v123, s[8:9] offset:1024
	global_load_dwordx4 v[18:21], v123, s[10:11] offset:1024
	s_waitcnt lgkmcnt(0)
	v_add_f32_e32 v88, v22, v23
	ds_bpermute_b32 v89, v120, v88
	global_load_dwordx4 v[26:29], v[30:31], off offset:16
	global_load_dwordx4 v[22:25], v[30:31], off
	global_load_dwordx4 v[34:37], v[32:33], off offset:16
	s_nop 0
	global_load_dwordx4 v[30:33], v[32:33], off
	s_waitcnt lgkmcnt(0)
	v_add_f32_e32 v116, v88, v89
	ds_bpermute_b32 v117, v121, v116
	s_waitcnt vmcnt(16)
	v_cndmask_b32_e32 v89, 0, v93, vcc
	s_waitcnt vmcnt(15)
	v_cndmask_b32_e32 v94, 0, v97, vcc
	v_cndmask_b32_e32 v97, 0, v98, vcc
	s_waitcnt lgkmcnt(0)
	v_add_f32_e32 v98, v116, v117
	v_fmamk_f32 v98, v98, 0x3c800000, v124
	v_rsq_f32_e32 v251, v98
	v_cndmask_b32_e32 v95, 0, v99, vcc
	s_waitcnt vmcnt(14)
	v_cndmask_b32_e32 v93, 1.0, v103, vcc
	v_cndmask_b32_e32 v88, 0, v91, vcc
	v_cndmask_b32_e32 v98, 1.0, v100, vcc
	v_cndmask_b32_e32 v91, 0, v92, vcc
	v_cndmask_b32_e32 v92, 1.0, v101, vcc
	v_cndmask_b32_e32 v99, 1.0, v102, vcc
	s_waitcnt vmcnt(13)
	v_cndmask_b32_e32 v101, 1.0, v107, vcc
	v_cndmask_b32_e32 v90, 0, v90, vcc
	v_cndmask_b32_e32 v96, 0, v96, vcc
	s_waitcnt vmcnt(12)
	v_and_b32_e32 v118, 0xffff0000, v68
	v_mov_b32_e32 v126, v118
	v_cndmask_b32_e32 v102, 1.0, v104, vcc
	v_and_b32_e32 v119, 0xffff0000, v69
	v_cndmask_b32_e32 v100, 1.0, v105, vcc
	v_cndmask_b32_e32 v103, 1.0, v106, vcc
	v_mov_b32_e32 v128, v119
	v_mov_b32_e32 v104, v251
	v_pk_mul_f32 v[106:107], v[104:105], v[108:109] op_sel_hi:[0,1]
	v_pk_mul_f32 v[106:107], v[86:87], v[106:107]
	v_pk_mul_f32 v[110:111], v[104:105], v[110:111] op_sel_hi:[0,1]
	ds_bpermute_b32 v108, v121, v106
	ds_bpermute_b32 v109, v121, v107
	v_pk_mul_f32 v[110:111], v[4:5], v[110:111]
	ds_bpermute_b32 v116, v121, v110
	ds_bpermute_b32 v117, v121, v111
	v_pk_mul_f32 v[106:107], v[102:103], v[106:107]
	s_waitcnt lgkmcnt(2)
	v_pk_mul_f32 v[108:109], v[70:71], v[108:109]
	s_nop 0
	v_pk_fma_f32 v[106:107], v[96:97], v[108:109], v[106:107]
	v_pk_mul_f32 v[108:109], v[100:101], v[110:111]
	s_waitcnt lgkmcnt(0)
	v_pk_mul_f32 v[110:111], v[70:71], v[116:117]
	v_lshlrev_b32_e32 v116, 16, v68
	v_pk_fma_f32 v[108:109], v[94:95], v[110:111], v[108:109]
	v_pk_mul_f32 v[110:111], v[104:105], v[112:113] op_sel_hi:[0,1]
	v_pk_mul_f32 v[110:111], v[6:7], v[110:111]
	ds_bpermute_b32 v112, v121, v110
	ds_bpermute_b32 v113, v121, v111
	v_pk_mul_f32 v[104:105], v[104:105], v[114:115] op_sel_hi:[0,1]
	v_pk_mul_f32 v[104:105], v[12:13], v[104:105]
	ds_bpermute_b32 v114, v121, v104
	ds_bpermute_b32 v115, v121, v105
	s_waitcnt lgkmcnt(2)
	v_pk_mul_f32 v[112:113], v[70:71], v[112:113]
	v_pk_mul_f32 v[108:109], v[108:109], s[80:81] op_sel_hi:[1,0]
	v_pk_mul_f32 v[112:113], v[90:91], v[112:113]
	v_mov_b32_e32 v127, v116
	v_pk_fma_f32 v[110:111], v[98:99], v[110:111], v[112:113]
	s_waitcnt lgkmcnt(0)
	v_pk_mul_f32 v[112:113], v[70:71], v[114:115]
	v_lshlrev_b32_e32 v117, 16, v69
	v_pk_mul_f32 v[112:113], v[88:89], v[112:113]
	v_pk_mul_f32 v[126:127], v[126:127], v[126:127]
	v_pk_fma_f32 v[104:105], v[92:93], v[104:105], v[112:113]
	v_bfe_u32 v112, v109, 16, 1
	v_pk_mul_f32 v[104:105], v[104:105], s[80:81] op_sel_hi:[1,0]
	v_bfe_u32 v113, v108, 16, 1
	v_bfe_u32 v114, v105, 16, 1
	v_bfe_u32 v115, v104, 16, 1
	v_add3_u32 v132, v108, v113, s33
	v_add3_u32 v133, v109, v112, s33
	v_lshlrev_b32_e32 v109, 16, v67
	v_lshlrev_b32_e32 v108, 16, v66
	v_and_b32_e32 v113, 0xffff0000, v67
	v_and_b32_e32 v112, 0xffff0000, v66
	v_add3_u32 v130, v104, v115, s33
	v_add3_u32 v131, v105, v114, s33
	v_pk_mul_f32 v[104:105], v[108:109], v[108:109]
	v_pk_mul_f32 v[114:115], v[112:113], v[112:113]
	v_mov_b32_e32 v129, v117
	v_add_f32_e32 v104, v104, v114
	v_add_f32_e32 v104, v105, v104
	v_add_f32_e32 v104, v115, v104
	v_add_f32_e32 v104, v127, v104
	v_pk_mul_f32 v[128:129], v[128:129], v[128:129]
	v_add_f32_e32 v104, v126, v104
	v_add_f32_e32 v104, v129, v104
	v_add_f32_e32 v104, v128, v104
	ds_bpermute_b32 v105, v1, v104
	v_pk_mul_f32 v[110:111], v[110:111], s[80:81] op_sel_hi:[1,0]
	v_pk_mul_f32 v[106:107], v[106:107], s[80:81] op_sel_hi:[1,0]
	v_bfe_u32 v114, v110, 16, 1
	v_bfe_u32 v115, v111, 16, 1
	s_waitcnt lgkmcnt(0)
	v_add_f32_e32 v104, v104, v105
	ds_bpermute_b32 v105, v120, v104
	v_add3_u32 v110, v110, v114, s33
	v_add3_u32 v111, v111, v115, s33
	v_bfe_u32 v126, v106, 16, 1
	v_bfe_u32 v127, v107, 16, 1
	s_waitcnt lgkmcnt(0)
	v_add_f32_e32 v104, v104, v105
	ds_bpermute_b32 v105, v121, v104
	v_add3_u32 v106, v106, v126, s33
	v_add3_u32 v107, v107, v127, s33
	v_lshrrev_b32_e32 v106, 16, v106
	v_lshrrev_b32_e32 v111, 16, v111
	s_waitcnt lgkmcnt(0)
	v_add_f32_e32 v104, v104, v105
	v_fmamk_f32 v104, v104, 0x3c800000, v124
	v_rsq_f32_e32 v252, v104
	v_lshrrev_b32_e32 v107, 16, v107
	v_lshrrev_b32_e32 v110, 16, v110
	v_and_or_b32 v104, v132, s23, v106
	v_and_or_b32 v105, v133, s23, v107
	v_and_or_b32 v107, v131, s23, v111
	v_and_or_b32 v106, v130, s23, v110
	v_lshl_add_u64 v[110:111], v[14:15], 0, s[78:79]
	global_store_dwordx4 v[110:111], v[104:107], off
	s_add_u32 s8, s37, s13
	s_addc_u32 s9, s3, 0
	v_mov_b32_e32 v126, v252
	v_pk_mul_f32 v[104:105], v[126:127], v[108:109] op_sel_hi:[0,1]
	v_pk_mul_f32 v[108:109], v[126:127], v[112:113] op_sel_hi:[0,1]
	v_pk_mul_f32 v[114:115], v[8:9], v[108:109]
	v_pk_mul_f32 v[108:109], v[126:127], v[116:117] op_sel_hi:[0,1]
	v_pk_mul_f32 v[116:117], v[126:127], v[118:119] op_sel_hi:[0,1]
	v_pk_mul_f32 v[106:107], v[2:3], v[104:105]
	v_pk_mul_f32 v[108:109], v[10:11], v[108:109]
	v_pk_mul_f32 v[116:117], v[16:17], v[116:117]
	ds_bpermute_b32 v104, v121, v106
	ds_bpermute_b32 v110, v121, v114
	ds_bpermute_b32 v105, v121, v107
	ds_bpermute_b32 v111, v121, v115
	ds_bpermute_b32 v112, v121, v108
	ds_bpermute_b32 v118, v121, v116
	ds_bpermute_b32 v113, v121, v109
	ds_bpermute_b32 v119, v121, v117
	s_lshl_b64 s[8:9], s[8:9], 7
	s_and_saveexec_b64 s[10:11], s[0:1]
	s_xor_b64 s[10:11], exec, s[10:11]
	s_cbranch_execnz .LBB0_377
	s_andn2_saveexec_b64 s[10:11], s[10:11]
	s_cbranch_execnz .LBB0_380

.LBB0_381:
	s_waitcnt vmcnt(8)
	v_lshlrev_b32_e32 v66, 16, v62
	v_and_b32_e32 v68, 0xffff0000, v62
	v_lshlrev_b32_e32 v67, 16, v63
	v_and_b32_e32 v69, 0xffff0000, v63
	v_pk_mul_f32 v[62:63], v[66:67], v[66:67]
	v_pk_mul_f32 v[90:91], v[68:69], v[68:69]
	v_lshlrev_b32_e32 v88, 16, v64
	v_and_b32_e32 v64, 0xffff0000, v64
	v_add_f32_e32 v62, v62, v90
	v_mov_b32_e32 v92, v64
	v_mov_b32_e32 v93, v88
	v_add_f32_e32 v62, v63, v62
	v_lshlrev_b32_e32 v89, 16, v65
	v_and_b32_e32 v65, 0xffff0000, v65
	v_pk_mul_f32 v[92:93], v[92:93], v[92:93]
	v_add_f32_e32 v62, v91, v62
	v_mov_b32_e32 v94, v65
	v_mov_b32_e32 v95, v89
	v_add_f32_e32 v62, v93, v62
	v_pk_mul_f32 v[94:95], v[94:95], v[94:95]
	v_add_f32_e32 v62, v92, v62
	v_add_f32_e32 v62, v95, v62
	v_add_f32_e32 v90, v94, v62
	ds_bpermute_b32 v91, v1, v90
	s_cmpk_lt_i32 s12, 0x4000
	s_cselect_b64 s[8:9], -1, 0
	s_and_b64 s[8:9], s[8:9], exec
	s_cselect_b32 s3, s22, 0xff
	s_waitcnt lgkmcnt(0)
	v_add_f32_e32 v90, v90, v91
	ds_bpermute_b32 v91, v120, v90
	s_and_b32 s3, s3, s12
	s_add_i32 s10, s3, 0x100
	s_cmpk_lt_i32 s12, 0x4000
	s_cselect_b64 s[8:9], -1, 0
	s_waitcnt lgkmcnt(0)
	v_add_f32_e32 v90, v90, v91
	s_and_b64 s[8:9], s[8:9], exec
	ds_bpermute_b32 v91, v121, v90
	s_cselect_b32 s13, s10, s3
	s_add_i32 s8, s12, 0xffffc000
	s_ashr_i32 s3, s12, 11
	s_lshr_b32 s10, s8, 8
	s_cmpk_lt_i32 s12, 0x4000
	s_cselect_b64 vcc, -1, 0
	v_cndmask_b32_e32 v63, 0, v61, vcc
	v_cndmask_b32_e32 v61, 0, v57, vcc
	v_cndmask_b32_e32 v57, 0, v56, vcc
	v_cndmask_b32_e32 v56, 0, v54, vcc
	v_cndmask_b32_e32 v54, 1.0, v51, vcc
	s_waitcnt lgkmcnt(0)
	v_add_f32_e32 v51, v90, v91
	s_and_b64 s[8:9], vcc, exec
	v_fmamk_f32 v51, v51, 0x3c800000, v124
	v_rsq_f32_e32 v253, v51
	v_cndmask_b32_e32 v62, 0, v59, vcc
	v_cndmask_b32_e32 v59, 0, v60, vcc
	v_cndmask_b32_e32 v60, 0, v55, vcc
	v_cndmask_b32_e32 v55, 1.0, v53, vcc
	s_cselect_b32 s12, s3, s10
	v_cndmask_b32_e32 v58, 0, v58, vcc
	v_cndmask_b32_e32 v53, 1.0, v49, vcc
	v_cndmask_b32_e32 v51, 1.0, v52, vcc
	v_cndmask_b32_e32 v50, 1.0, v50, vcc
	v_cndmask_b32_e32 v46, 1.0, v46, vcc
	s_waitcnt vmcnt(6)
	v_and_b32_e32 v94, 0xffff0000, v44
	v_mov_b32_e32 v96, v94
	v_cndmask_b32_e32 v52, 1.0, v47, vcc
	v_cndmask_b32_e32 v47, 1.0, v48, vcc
	v_and_b32_e32 v95, 0xffff0000, v45
	v_mov_b32_e32 v98, v95
	s_mul_hi_i32 s3, s12, 0x900
	v_mov_b32_e32 v48, v253
	v_pk_mul_f32 v[66:67], v[48:49], v[66:67] op_sel_hi:[0,1]
	v_pk_mul_f32 v[66:67], v[86:87], v[66:67]
	v_pk_mul_f32 v[68:69], v[48:49], v[68:69] op_sel_hi:[0,1]
	ds_bpermute_b32 v90, v121, v66
	ds_bpermute_b32 v91, v121, v67
	v_pk_mul_f32 v[68:69], v[4:5], v[68:69]
	ds_bpermute_b32 v92, v121, v68
	ds_bpermute_b32 v93, v121, v69
	v_pk_mul_f32 v[88:89], v[48:49], v[88:89] op_sel_hi:[0,1]
	v_pk_mul_f32 v[48:49], v[48:49], v[64:65] op_sel_hi:[0,1]
	v_pk_mul_f32 v[48:49], v[12:13], v[48:49]
	v_pk_mul_f32 v[66:67], v[46:47], v[66:67]
	s_waitcnt lgkmcnt(2)
	v_pk_mul_f32 v[90:91], v[70:71], v[90:91]
	ds_bpermute_b32 v64, v121, v48
	ds_bpermute_b32 v65, v121, v49
	v_pk_fma_f32 v[66:67], v[56:57], v[90:91], v[66:67]
	v_pk_mul_f32 v[68:69], v[52:53], v[68:69]
	s_waitcnt lgkmcnt(2)
	v_pk_mul_f32 v[90:91], v[70:71], v[92:93]
	v_pk_mul_f32 v[88:89], v[6:7], v[88:89]
	v_pk_fma_f32 v[68:69], v[60:61], v[90:91], v[68:69]
	ds_bpermute_b32 v90, v121, v88
	ds_bpermute_b32 v91, v121, v89
	s_waitcnt lgkmcnt(2)
	v_pk_mul_f32 v[64:65], v[70:71], v[64:65]
	v_pk_mul_f32 v[68:69], v[68:69], s[80:81] op_sel_hi:[1,0]
	v_pk_mul_f32 v[64:65], v[62:63], v[64:65]
	v_lshlrev_b32_e32 v92, 16, v44
	s_waitcnt lgkmcnt(0)
	v_pk_mul_f32 v[90:91], v[70:71], v[90:91]
	v_pk_fma_f32 v[48:49], v[54:55], v[48:49], v[64:65]
	v_pk_mul_f32 v[90:91], v[58:59], v[90:91]
	v_pk_mul_f32 v[48:49], v[48:49], s[80:81] op_sel_hi:[1,0]
	v_pk_fma_f32 v[88:89], v[50:51], v[88:89], v[90:91]
	v_bfe_u32 v64, v69, 16, 1
	v_bfe_u32 v65, v68, 16, 1
	v_bfe_u32 v90, v49, 16, 1
	v_bfe_u32 v91, v48, 16, 1
	v_add3_u32 v100, v48, v91, s33
	v_add3_u32 v101, v49, v90, s33
	v_add3_u32 v102, v68, v65, s33
	v_add3_u32 v103, v69, v64, s33
	v_lshlrev_b32_e32 v49, 16, v43
	v_lshlrev_b32_e32 v48, 16, v42
	v_and_b32_e32 v69, 0xffff0000, v43
	v_and_b32_e32 v68, 0xffff0000, v42
	v_pk_mul_f32 v[64:65], v[48:49], v[48:49]
	v_pk_mul_f32 v[90:91], v[68:69], v[68:69]
	v_mov_b32_e32 v97, v92
	v_add_f32_e32 v64, v64, v90
	v_add_f32_e32 v64, v65, v64
	v_lshlrev_b32_e32 v93, 16, v45
	v_pk_mul_f32 v[96:97], v[96:97], v[96:97]
	v_add_f32_e32 v64, v91, v64
	v_mov_b32_e32 v99, v93
	v_add_f32_e32 v64, v97, v64
	v_pk_mul_f32 v[98:99], v[98:99], v[98:99]
	v_add_f32_e32 v64, v96, v64
	v_add_f32_e32 v64, v99, v64
	v_add_f32_e32 v64, v98, v64
	ds_bpermute_b32 v65, v1, v64
	v_pk_mul_f32 v[88:89], v[88:89], s[80:81] op_sel_hi:[1,0]
	v_pk_mul_f32 v[66:67], v[66:67], s[80:81] op_sel_hi:[1,0]
	v_bfe_u32 v90, v88, 16, 1
	v_bfe_u32 v91, v89, 16, 1
	s_waitcnt lgkmcnt(0)
	v_add_f32_e32 v64, v64, v65
	ds_bpermute_b32 v65, v120, v64
	v_add3_u32 v88, v88, v90, s33
	v_add3_u32 v89, v89, v91, s33
	v_bfe_u32 v96, v66, 16, 1
	v_bfe_u32 v97, v67, 16, 1
	s_waitcnt lgkmcnt(0)
	v_add_f32_e32 v64, v64, v65
	ds_bpermute_b32 v65, v121, v64
	v_add3_u32 v66, v66, v96, s33
	v_add3_u32 v67, v67, v97, s33
	v_lshrrev_b32_e32 v66, 16, v66
	v_lshrrev_b32_e32 v89, 16, v89
	s_waitcnt lgkmcnt(0)
	v_add_f32_e32 v64, v64, v65
	v_fmamk_f32 v64, v64, 0x3c800000, v124
	v_rsq_f32_e32 v254, v64
	v_lshrrev_b32_e32 v67, 16, v67
	v_lshrrev_b32_e32 v88, 16, v88
	v_and_or_b32 v64, v102, s23, v66
	v_and_or_b32 v65, v103, s23, v67
	v_and_or_b32 v67, v101, s23, v89
	s_mulk_i32 s12, 0x900
	v_and_or_b32 v66, v100, s23, v88
	v_lshl_add_u64 v[88:89], v[14:15], 0, s[74:75]
	global_store_dwordx4 v[88:89], v[64:67], off
	s_add_u32 s8, s12, s13
	s_addc_u32 s9, s3, 0
	v_mov_b32_e32 v96, v254
	v_pk_mul_f32 v[66:67], v[96:97], v[68:69] op_sel_hi:[0,1]
	v_pk_mul_f32 v[48:49], v[96:97], v[48:49] op_sel_hi:[0,1]
	v_pk_mul_f32 v[90:91], v[8:9], v[66:67]
	v_pk_mul_f32 v[66:67], v[96:97], v[92:93] op_sel_hi:[0,1]
	v_pk_mul_f32 v[92:93], v[96:97], v[94:95] op_sel_hi:[0,1]
	v_pk_mul_f32 v[64:65], v[2:3], v[48:49]
	v_pk_mul_f32 v[66:67], v[10:11], v[66:67]
	v_pk_mul_f32 v[92:93], v[16:17], v[92:93]
	ds_bpermute_b32 v48, v121, v64
	ds_bpermute_b32 v68, v121, v90
	ds_bpermute_b32 v49, v121, v65
	ds_bpermute_b32 v69, v121, v91
	ds_bpermute_b32 v88, v121, v66
	ds_bpermute_b32 v94, v121, v92
	ds_bpermute_b32 v89, v121, v67
	ds_bpermute_b32 v95, v121, v93
	s_lshl_b64 s[8:9], s[8:9], 7
	s_and_saveexec_b64 s[10:11], s[0:1]
	s_xor_b64 s[10:11], exec, s[10:11]
	s_cbranch_execz .LBB0_385
	s_and_saveexec_b64 s[84:85], s[6:7]
	s_cbranch_execz .LBB0_384
	v_lshl_add_u64 v[46:47], s[8:9], 1, v[80:81]
	global_store_dwordx4 v[46:47], v[42:45], off offset:-256

.LBB0_388:
	s_waitcnt vmcnt(6)
	v_lshlrev_b32_e32 v42, 16, v38
	v_and_b32_e32 v44, 0xffff0000, v38
	v_lshlrev_b32_e32 v43, 16, v39
	v_and_b32_e32 v45, 0xffff0000, v39
	v_pk_mul_f32 v[38:39], v[42:43], v[42:43]
	s_waitcnt lgkmcnt(5)
	v_pk_mul_f32 v[48:49], v[44:45], v[44:45]
	v_lshlrev_b32_e32 v46, 16, v40
	v_and_b32_e32 v40, 0xffff0000, v40
	v_add_f32_e32 v38, v38, v48
	v_mov_b32_e32 v50, v40
	v_mov_b32_e32 v51, v46
	v_add_f32_e32 v38, v39, v38
	v_lshlrev_b32_e32 v47, 16, v41
	v_and_b32_e32 v41, 0xffff0000, v41
	v_pk_mul_f32 v[50:51], v[50:51], v[50:51]
	v_add_f32_e32 v38, v49, v38
	v_mov_b32_e32 v52, v41
	v_mov_b32_e32 v53, v47
	v_add_f32_e32 v38, v51, v38
	v_pk_mul_f32 v[52:53], v[52:53], v[52:53]
	v_add_f32_e32 v38, v50, v38
	v_add_f32_e32 v38, v53, v38
	v_add_f32_e32 v48, v52, v38
	ds_bpermute_b32 v49, v1, v48
	s_cmpk_lt_i32 s82, 0x4000
	s_cselect_b64 s[8:9], -1, 0
	s_and_b64 s[8:9], s[8:9], exec
	s_cselect_b32 s3, s22, 0xff
	s_waitcnt lgkmcnt(0)
	v_add_f32_e32 v48, v48, v49
	ds_bpermute_b32 v49, v120, v48
	s_and_b32 s3, s3, s82
	s_add_i32 s10, s3, 0x100
	s_cmpk_lt_i32 s82, 0x4000
	s_cselect_b64 s[8:9], -1, 0
	s_waitcnt lgkmcnt(0)
	v_add_f32_e32 v48, v48, v49
	s_and_b64 s[8:9], s[8:9], exec
	ds_bpermute_b32 v49, v121, v48
	s_cselect_b32 s12, s10, s3
	s_add_i32 s8, s82, 0xffffc000
	s_ashr_i32 s3, s82, 11
	s_lshr_b32 s10, s8, 8
	s_cmpk_lt_i32 s82, 0x4000
	s_cselect_b64 vcc, -1, 0
	s_waitcnt vmcnt(2)
	v_cndmask_b32_e32 v39, 0, v37, vcc
	s_waitcnt vmcnt(1)
	v_cndmask_b32_e32 v37, 0, v33, vcc
	v_cndmask_b32_e32 v33, 0, v32, vcc
	v_cndmask_b32_e32 v32, 0, v30, vcc
	v_cndmask_b32_e32 v30, 1.0, v27, vcc
	s_waitcnt lgkmcnt(0)
	v_add_f32_e32 v27, v48, v49
	s_and_b64 s[8:9], vcc, exec
	v_fmamk_f32 v27, v27, 0x3c800000, v124
	v_rsq_f32_e32 v251, v27
	v_cndmask_b32_e32 v38, 0, v35, vcc
	v_cndmask_b32_e32 v35, 0, v36, vcc
	v_cndmask_b32_e32 v36, 0, v31, vcc
	v_cndmask_b32_e32 v31, 1.0, v29, vcc
	s_cselect_b32 s13, s3, s10
	v_cndmask_b32_e32 v34, 0, v34, vcc
	v_cndmask_b32_e32 v29, 1.0, v25, vcc
	v_cndmask_b32_e32 v27, 1.0, v28, vcc
	v_cndmask_b32_e32 v26, 1.0, v26, vcc
	v_cndmask_b32_e32 v22, 1.0, v22, vcc
	v_and_b32_e32 v52, 0xffff0000, v20
	v_mov_b32_e32 v54, v52
	v_cndmask_b32_e32 v28, 1.0, v23, vcc
	v_cndmask_b32_e32 v23, 1.0, v24, vcc
	v_and_b32_e32 v53, 0xffff0000, v21
	v_mov_b32_e32 v56, v53
	s_ashr_i32 s83, s82, 31
	v_mov_b32_e32 v24, v251
	v_pk_mul_f32 v[42:43], v[24:25], v[42:43] op_sel_hi:[0,1]
	v_pk_mul_f32 v[42:43], v[86:87], v[42:43]
	v_pk_mul_f32 v[44:45], v[24:25], v[44:45] op_sel_hi:[0,1]
	ds_bpermute_b32 v48, v121, v42
	ds_bpermute_b32 v49, v121, v43
	v_pk_mul_f32 v[44:45], v[4:5], v[44:45]
	ds_bpermute_b32 v50, v121, v44
	ds_bpermute_b32 v51, v121, v45
	v_pk_mul_f32 v[46:47], v[24:25], v[46:47] op_sel_hi:[0,1]
	v_pk_mul_f32 v[24:25], v[24:25], v[40:41] op_sel_hi:[0,1]
	v_pk_mul_f32 v[24:25], v[12:13], v[24:25]
	v_pk_mul_f32 v[42:43], v[22:23], v[42:43]
	s_waitcnt lgkmcnt(2)
	v_pk_mul_f32 v[48:49], v[70:71], v[48:49]
	ds_bpermute_b32 v40, v121, v24
	ds_bpermute_b32 v41, v121, v25
	v_pk_fma_f32 v[42:43], v[32:33], v[48:49], v[42:43]
	v_pk_mul_f32 v[44:45], v[28:29], v[44:45]
	s_waitcnt lgkmcnt(2)
	v_pk_mul_f32 v[48:49], v[70:71], v[50:51]
	v_pk_mul_f32 v[46:47], v[6:7], v[46:47]
	v_pk_fma_f32 v[44:45], v[36:37], v[48:49], v[44:45]
	ds_bpermute_b32 v48, v121, v46
	ds_bpermute_b32 v49, v121, v47
	s_waitcnt lgkmcnt(2)
	v_pk_mul_f32 v[40:41], v[70:71], v[40:41]
	v_pk_mul_f32 v[44:45], v[44:45], s[80:81] op_sel_hi:[1,0]
	v_pk_mul_f32 v[40:41], v[38:39], v[40:41]
	v_lshlrev_b32_e32 v50, 16, v20
	s_waitcnt lgkmcnt(0)
	v_pk_mul_f32 v[48:49], v[70:71], v[48:49]
	v_pk_fma_f32 v[24:25], v[30:31], v[24:25], v[40:41]
	v_pk_mul_f32 v[48:49], v[34:35], v[48:49]
	v_pk_mul_f32 v[24:25], v[24:25], s[80:81] op_sel_hi:[1,0]
	v_pk_fma_f32 v[46:47], v[26:27], v[46:47], v[48:49]
	v_bfe_u32 v40, v45, 16, 1
	v_bfe_u32 v41, v44, 16, 1
	v_bfe_u32 v48, v25, 16, 1
	v_bfe_u32 v49, v24, 16, 1
	v_add3_u32 v58, v24, v49, s33
	v_add3_u32 v59, v25, v48, s33
	v_add3_u32 v60, v44, v41, s33
	v_add3_u32 v61, v45, v40, s33
	v_lshlrev_b32_e32 v25, 16, v19
	v_lshlrev_b32_e32 v24, 16, v18
	v_and_b32_e32 v45, 0xffff0000, v19
	v_and_b32_e32 v44, 0xffff0000, v18
	v_pk_mul_f32 v[40:41], v[24:25], v[24:25]
	v_pk_mul_f32 v[48:49], v[44:45], v[44:45]
	v_mov_b32_e32 v55, v50
	v_add_f32_e32 v40, v40, v48
	v_add_f32_e32 v40, v41, v40
	v_lshlrev_b32_e32 v51, 16, v21
	v_pk_mul_f32 v[54:55], v[54:55], v[54:55]
	v_add_f32_e32 v40, v49, v40
	v_mov_b32_e32 v57, v51
	v_add_f32_e32 v40, v55, v40
	v_pk_mul_f32 v[56:57], v[56:57], v[56:57]
	v_add_f32_e32 v40, v54, v40
	v_add_f32_e32 v40, v57, v40
	v_add_f32_e32 v40, v56, v40
	ds_bpermute_b32 v41, v1, v40
	v_pk_mul_f32 v[42:43], v[42:43], s[80:81] op_sel_hi:[1,0]
	v_pk_mul_f32 v[46:47], v[46:47], s[80:81] op_sel_hi:[1,0]
	v_bfe_u32 v48, v42, 16, 1
	v_bfe_u32 v49, v43, 16, 1
	s_waitcnt lgkmcnt(0)
	v_add_f32_e32 v40, v40, v41
	ds_bpermute_b32 v41, v120, v40
	v_add3_u32 v42, v42, v48, s33
	v_add3_u32 v43, v43, v49, s33
	v_bfe_u32 v62, v46, 16, 1
	v_bfe_u32 v63, v47, 16, 1
	s_waitcnt lgkmcnt(0)
	v_add_f32_e32 v48, v40, v41
	ds_bpermute_b32 v49, v121, v48
	v_lshrrev_b32_e32 v40, 16, v42
	v_lshrrev_b32_e32 v41, 16, v43
	v_add3_u32 v46, v46, v62, s33
	v_add3_u32 v47, v47, v63, s33
	s_waitcnt lgkmcnt(0)
	v_add_f32_e32 v42, v48, v49
	v_fmamk_f32 v42, v42, 0x3c800000, v124
	v_rsq_f32_e32 v252, v42
	v_lshrrev_b32_e32 v46, 16, v46
	v_lshrrev_b32_e32 v47, 16, v47
	v_and_or_b32 v42, v58, s23, v46
	v_and_or_b32 v43, v59, s23, v47
	v_and_or_b32 v41, v61, s23, v41
	v_and_or_b32 v40, v60, s23, v40
	s_mul_hi_i32 s3, s13, 0x900
	s_mulk_i32 s13, 0x900
	s_lshl_b64 s[8:9], s[82:83], 11
	v_lshl_add_u64 v[46:47], v[76:77], 0, s[8:9]
	global_store_dwordx4 v[46:47], v[40:43], off
	s_add_u32 s8, s13, s12
	s_addc_u32 s9, s3, 0
	v_mov_b32_e32 v54, v252
	v_pk_mul_f32 v[42:43], v[54:55], v[44:45] op_sel_hi:[0,1]
	v_pk_mul_f32 v[24:25], v[54:55], v[24:25] op_sel_hi:[0,1]
	v_pk_mul_f32 v[48:49], v[8:9], v[42:43]
	v_pk_mul_f32 v[42:43], v[54:55], v[50:51] op_sel_hi:[0,1]
	v_pk_mul_f32 v[50:51], v[54:55], v[52:53] op_sel_hi:[0,1]
	v_pk_mul_f32 v[40:41], v[2:3], v[24:25]
	v_pk_mul_f32 v[42:43], v[10:11], v[42:43]
	v_pk_mul_f32 v[50:51], v[16:17], v[50:51]
	ds_bpermute_b32 v24, v121, v40
	ds_bpermute_b32 v44, v121, v48
	ds_bpermute_b32 v25, v121, v41
	ds_bpermute_b32 v45, v121, v49
	ds_bpermute_b32 v46, v121, v42
	ds_bpermute_b32 v52, v121, v50
	ds_bpermute_b32 v47, v121, v43
	ds_bpermute_b32 v53, v121, v51
	s_lshl_b64 s[8:9], s[8:9], 7
	s_and_saveexec_b64 s[10:11], s[0:1]
	s_xor_b64 s[10:11], exec, s[10:11]
	s_cbranch_execz .LBB0_392
	s_and_saveexec_b64 s[82:83], s[6:7]
	s_cbranch_execz .LBB0_391
	v_lshl_add_u64 v[22:23], s[8:9], 1, v[80:81]
	global_store_dwordx4 v[22:23], v[18:21], off offset:-256

.LBB0_825:
	s_cmpk_lg_i32 s94, 0x100
	s_cbranch_scc1 .Ltr2_done
	v_readlane_b32 s0, v250, 17
	v_mov_b32_e32 v6, v0
	v_readlane_b32 s1, v250, 18
	s_andn2_b64 vcc, exec, s[0:1]
	v_readfirstlane_b32 s0, v6
	s_cbranch_vccnz .Ltr2_done
	s_sub_i32 s1, s2, s97
	s_ashr_i32 s0, s0, 6
	s_lshl_b32 s1, s1, 3
	s_add_i32 s8, s0, s1
	s_cmpk_gt_i32 s8, 0x77f
	s_cbranch_scc1 .Ltr2_done
	s_lshl_b32 s0, s0, 14
	v_and_b32_e32 v16, 31, v6
	s_add_i32 s0, s0, 0
	s_waitcnt lgkmcnt(0)
	v_mov_b32_e32 v3, 0
	v_lshlrev_b32_e32 v2, 2, v16
	v_lshl_add_u64 v[4:5], s[58:59], 0, v[2:3]
	v_add_u32_e32 v15, s0, v2
	v_lshlrev_b32_e32 v2, 3, v6
	v_and_b32_e32 v2, 56, v2
	v_bfe_u32 v10, v6, 3, 3
	v_mul_u32_u24_e32 v11, 0x84, v2
	v_lshlrev_b32_e32 v2, 1, v2
	v_lshl_add_u64 v[8:9], s[34:35], 0, v[2:3]
	v_lshlrev_b32_e32 v2, 2, v10
	v_bfe_u32 v1, v6, 5, 1
	v_add3_u32 v11, s0, v11, v2
	s_lshl_b32 s0, s94, 8
	s_lshl_b32 s3, s97, 8
	v_mul_u32_u24_e32 v17, 0x84, v1
	s_mov_b64 s[6:7], 0x2780000
	s_sub_i32 s11, s0, s3
	s_lshl_b32 s0, s8, 1
	s_sub_i32 s1, s94, s97
	s_mov_b64 s[4:5], 0xb00000
	v_lshl_add_u64 v[6:7], v[8:9], 0, s[6:7]
	s_mov_b64 s[6:7], 0x1700000
	s_add_i32 s12, s0, 0x1ea00
	s_lshl_b32 s0, s94, 4
	s_lshl_b32 s3, s97, 4
	v_add_u32_e32 v15, v15, v17
	s_lshl_b32 s9, s1, 3
	s_mov_b32 s1, 0
	v_lshl_add_u64 v[4:5], v[4:5], 0, s[4:5]
	v_or_b32_e32 v12, 8, v10
	v_or_b32_e32 v13, 16, v10
	v_or_b32_e32 v14, 24, v10
	v_lshl_add_u64 v[8:9], v[8:9], 0, s[6:7]
	s_lshl_b32 s10, s8, 5
	s_sub_i32 s13, s0, s3
	s_movk_i32 s19, 0x7fff
	s_mov_b32 s20, 0xffff0000
	v_lshlrev_b32_e32 v2, 2, v16
	s_movk_i32 s21, 0x2c00
	v_add_u32_e32 v16, 0x400, v15
	v_add_u32_e32 v17, 0x800, v15
	v_add_u32_e32 v18, 0xc00, v15
	v_add_u32_e32 v19, 0x1000, v15
	v_add_u32_e32 v20, 0x1400, v15
	v_add_u32_e32 v21, 0x1800, v15
	v_add_u32_e32 v22, 0x1c00, v15
	s_branch .Ltr2_loop
.Ltr2_next:
	s_add_i32 s8, s8, s9
	s_add_i32 s10, s10, s11
	s_add_i32 s12, s12, s13
	s_cmpk_lt_i32 s8, 0x780
	s_cbranch_scc0 .Ltr2_done

.Ltr2_b:
	s_andn2_b64 vcc, exec, s[6:7]
	s_cbranch_vccnz .Ltr2_next
	s_add_i32 s0, s8, 0xfffffa80
	s_cmpk_gt_i32 s8, 0x57f
	s_cselect_b32 s0, s0, s8
	s_mul_hi_i32 s6, s0, 0x2e8ba2e9
	s_cselect_b32 s3, 0x80, 0
	s_cselect_b32 s7, s57, s55
	s_cselect_b32 s24, s56, s54
	s_lshr_b32 s22, s6, 31
	s_ashr_i32 s6, s6, 4
	s_add_i32 s6, s6, s22
	s_mul_i32 s22, s6, 0x58
	s_sub_i32 s0, s0, s22
	s_lshl_b32 s22, s0, 5
	s_lshl_b32 s0, s0, 6
	s_and_b32 s23, s22, 0x60
	s_and_b32 s0, s0, 0xffffff00
	s_or_b32 s3, s23, s3
	s_ashr_i32 s23, s22, 31
	s_lshl_b32 s6, s6, 6
	s_or_b32 s0, s3, s0
	s_lshl_b64 s[22:23], s[22:23], 2
	s_add_u32 s22, s24, s22
	s_addc_u32 s23, s7, s23
	v_or_b32_e32 v23, s6, v1
	v_lshl_add_u64 v[24:25], s[22:23], 0, v[2:3]
	v_lshl_add_u64 v[24:25], v[24:25], 0, s[4:5]
	v_or_b32_e32 v28, 2, v23
	v_or_b32_e32 v30, 4, v23
	v_or_b32_e32 v32, 6, v23
	v_or_b32_e32 v34, 8, v23
	v_or_b32_e32 v36, 10, v23
	v_or_b32_e32 v38, 12, v23
	v_or_b32_e32 v40, 14, v23
	v_mad_i64_i32 v[26:27], s[22:23], v23, s21, v[24:25]
	v_mad_i64_i32 v[28:29], s[22:23], v28, s21, v[24:25]
	v_mad_i64_i32 v[30:31], s[22:23], v30, s21, v[24:25]
	v_mad_i64_i32 v[32:33], s[22:23], v32, s21, v[24:25]
	v_mad_i64_i32 v[34:35], s[22:23], v34, s21, v[24:25]
	v_mad_i64_i32 v[36:37], s[22:23], v36, s21, v[24:25]
	v_mad_i64_i32 v[38:39], s[22:23], v38, s21, v[24:25]
	v_mad_i64_i32 v[40:41], s[22:23], v40, s21, v[24:25]
	global_load_dword v42, v[26:27], off nt
	global_load_dword v43, v[28:29], off nt
	global_load_dword v44, v[30:31], off nt
	global_load_dword v45, v[32:33], off nt
	global_load_dword v46, v[34:35], off nt
	global_load_dword v47, v[36:37], off nt
	global_load_dword v48, v[38:39], off nt
	global_load_dword v49, v[40:41], off nt
	v_or_b32_e32 v26, 16, v23
	v_or_b32_e32 v28, 18, v23
	v_or_b32_e32 v30, 20, v23
	v_or_b32_e32 v32, 22, v23
	v_or_b32_e32 v34, 24, v23
	v_or_b32_e32 v36, 26, v23
	v_or_b32_e32 v38, 28, v23
	v_or_b32_e32 v40, 30, v23
	v_mad_i64_i32 v[26:27], s[22:23], v26, s21, v[24:25]
	v_mad_i64_i32 v[28:29], s[22:23], v28, s21, v[24:25]
	v_mad_i64_i32 v[30:31], s[22:23], v30, s21, v[24:25]
	v_mad_i64_i32 v[32:33], s[22:23], v32, s21, v[24:25]
	v_mad_i64_i32 v[34:35], s[22:23], v34, s21, v[24:25]
	v_mad_i64_i32 v[36:37], s[22:23], v36, s21, v[24:25]
	v_mad_i64_i32 v[38:39], s[22:23], v38, s21, v[24:25]
	v_mad_i64_i32 v[40:41], s[22:23], v40, s21, v[24:25]
	global_load_dword v50, v[26:27], off nt
	global_load_dword v51, v[28:29], off nt
	global_load_dword v52, v[30:31], off nt
	global_load_dword v53, v[32:33], off nt
	global_load_dword v54, v[34:35], off nt
	global_load_dword v55, v[36:37], off nt
	global_load_dword v56, v[38:39], off nt
	global_load_dword v57, v[40:41], off nt
	v_or_b32_e32 v26, 32, v23
	v_or_b32_e32 v28, 34, v23
	v_or_b32_e32 v30, 36, v23
	v_or_b32_e32 v32, 38, v23
	v_or_b32_e32 v34, 40, v23
	v_or_b32_e32 v36, 42, v23
	v_or_b32_e32 v38, 44, v23
	v_or_b32_e32 v40, 46, v23
	v_mad_i64_i32 v[26:27], s[22:23], v26, s21, v[24:25]
	v_mad_i64_i32 v[28:29], s[22:23], v28, s21, v[24:25]
	v_mad_i64_i32 v[30:31], s[22:23], v30, s21, v[24:25]
	v_mad_i64_i32 v[32:33], s[22:23], v32, s21, v[24:25]
	v_mad_i64_i32 v[34:35], s[22:23], v34, s21, v[24:25]
	v_mad_i64_i32 v[36:37], s[22:23], v36, s21, v[24:25]
	v_mad_i64_i32 v[38:39], s[22:23], v38, s21, v[24:25]
	v_mad_i64_i32 v[40:41], s[22:23], v40, s21, v[24:25]
	global_load_dword v58, v[26:27], off nt
	global_load_dword v59, v[28:29], off nt
	global_load_dword v60, v[30:31], off nt
	global_load_dword v61, v[32:33], off nt
	global_load_dword v62, v[34:35], off nt
	global_load_dword v63, v[36:37], off nt
	global_load_dword v64, v[38:39], off nt
	s_nop 0
	global_load_dword v40, v[40:41], off nt
	v_or_b32_e32 v26, 48, v23
	v_or_b32_e32 v28, 50, v23
	v_or_b32_e32 v30, 52, v23
	v_or_b32_e32 v32, 54, v23
	v_or_b32_e32 v34, 56, v23
	v_or_b32_e32 v36, 58, v23
	v_or_b32_e32 v38, 60, v23
	v_or_b32_e32 v23, 62, v23
	v_mad_i64_i32 v[26:27], s[22:23], v26, s21, v[24:25]
	v_mad_i64_i32 v[28:29], s[22:23], v28, s21, v[24:25]
	v_mad_i64_i32 v[30:31], s[22:23], v30, s21, v[24:25]
	v_mad_i64_i32 v[32:33], s[22:23], v32, s21, v[24:25]
	v_mad_i64_i32 v[34:35], s[22:23], v34, s21, v[24:25]
	v_mad_i64_i32 v[36:37], s[22:23], v36, s21, v[24:25]
	v_mad_i64_i32 v[38:39], s[22:23], v38, s21, v[24:25]
	v_mad_i64_i32 v[24:25], s[22:23], v23, s21, v[24:25]
	global_load_dword v23, v[26:27], off nt
	s_nop 0
	global_load_dword v26, v[28:29], off nt
	global_load_dword v27, v[30:31], off nt
	s_nop 0
	global_load_dword v28, v[32:33], off nt
	global_load_dword v29, v[34:35], off nt
	global_load_dword v30, v[36:37], off nt
	global_load_dword v31, v[38:39], off nt
	s_nop 0
	global_load_dword v24, v[24:25], off nt
	s_waitcnt vmcnt(0)
	ds_write2_b32 v15, v42, v43 offset1:66
	ds_write2_b32 v15, v44, v45 offset0:132 offset1:198
	ds_write2_b32 v16, v46, v47 offset0:8 offset1:74
	ds_write2_b32 v16, v48, v49 offset0:140 offset1:206
	ds_write2_b32 v17, v50, v51 offset0:16 offset1:82
	ds_write2_b32 v17, v52, v53 offset0:148 offset1:214
	ds_write2_b32 v18, v54, v55 offset0:24 offset1:90
	ds_write2_b32 v18, v56, v57 offset0:156 offset1:222
	ds_write2_b32 v19, v58, v59 offset0:32 offset1:98
	ds_write2_b32 v19, v60, v61 offset0:164 offset1:230
	ds_write2_b32 v20, v62, v63 offset0:40 offset1:106
	ds_write2_b32 v20, v64, v40 offset0:172 offset1:238
	ds_write2_b32 v21, v23, v26 offset0:48 offset1:114
	ds_write2_b32 v21, v27, v28 offset0:180 offset1:246
	ds_write2_b32 v22, v29, v30 offset0:56 offset1:122
	ds_write2_b32 v22, v31, v24 offset0:188 offset1:254
	s_waitcnt lgkmcnt(0)
	ds_read2_b32 v[28:29], v11 offset1:8
	ds_read2_b32 v[32:33], v11 offset0:33 offset1:41
	ds_read2_b32 v[34:35], v11 offset0:66 offset1:74
	ds_read2_b32 v[36:37], v11 offset0:99 offset1:107
	ds_read2_b32 v[38:39], v11 offset0:132 offset1:140
	s_waitcnt lgkmcnt(4)
	v_bfe_u32 v23, v28, 16, 1
	v_add3_u32 v23, v28, v23, s19
	s_waitcnt lgkmcnt(3)
	v_bfe_u32 v24, v32, 16, 1
	v_lshrrev_b32_e32 v23, 16, v23
	v_add3_u32 v24, v32, v24, s19
	ds_read2_b32 v[40:41], v11 offset0:165 offset1:173
	v_and_or_b32 v24, v24, s20, v23
	s_waitcnt lgkmcnt(3)
	v_bfe_u32 v23, v34, 16, 1
	v_add3_u32 v23, v34, v23, s19
	s_waitcnt lgkmcnt(2)
	v_bfe_u32 v25, v36, 16, 1
	ds_read2_b32 v[42:43], v11 offset0:198 offset1:206
	v_lshrrev_b32_e32 v23, 16, v23
	v_add3_u32 v25, v36, v25, s19
	ds_read2_b32 v[44:45], v11 offset0:231 offset1:239
	v_and_or_b32 v25, v25, s20, v23
	s_waitcnt lgkmcnt(3)
	v_bfe_u32 v23, v38, 16, 1
	v_add3_u32 v23, v38, v23, s19
	s_waitcnt lgkmcnt(2)
	v_bfe_u32 v26, v40, 16, 1
	v_lshrrev_b32_e32 v23, 16, v23
	v_add3_u32 v26, v40, v26, s19
	v_and_or_b32 v26, v26, s20, v23
	s_waitcnt lgkmcnt(1)
	v_bfe_u32 v23, v42, 16, 1
	v_or_b32_e32 v46, s0, v10
	s_ashr_i32 s7, s6, 31
	v_add3_u32 v23, v42, v23, s19
	s_waitcnt lgkmcnt(0)
	v_bfe_u32 v27, v44, 16, 1
	v_ashrrev_i32_e32 v47, 31, v46
	v_lshl_add_u64 v[30:31], s[6:7], 1, v[8:9]
	v_lshrrev_b32_e32 v23, 16, v23
	v_add3_u32 v27, v44, v27, s19
	v_lshlrev_b64 v[46:47], 11, v[46:47]
	v_and_or_b32 v27, v27, s20, v23
	v_lshl_add_u64 v[46:47], v[30:31], 0, v[46:47]
	v_bfe_u32 v23, v29, 16, 1
	global_store_dwordx4 v[46:47], v[24:27], off
	v_add3_u32 v23, v29, v23, s19
	v_lshrrev_b32_e32 v23, 16, v23
	v_bfe_u32 v24, v33, 16, 1
	v_add3_u32 v24, v33, v24, s19
	v_and_or_b32 v24, v24, s20, v23
	v_bfe_u32 v23, v35, 16, 1
	v_add3_u32 v23, v35, v23, s19
	v_bfe_u32 v25, v37, 16, 1
	v_lshrrev_b32_e32 v23, 16, v23
	v_add3_u32 v25, v37, v25, s19
	v_and_or_b32 v25, v25, s20, v23
	v_bfe_u32 v23, v39, 16, 1
	v_add3_u32 v23, v39, v23, s19
	v_bfe_u32 v26, v41, 16, 1
	v_lshrrev_b32_e32 v23, 16, v23
	v_add3_u32 v26, v41, v26, s19
	v_and_or_b32 v26, v26, s20, v23
	v_bfe_u32 v23, v43, 16, 1
	v_or_b32_e32 v28, s0, v12
	v_add3_u32 v23, v43, v23, s19
	v_bfe_u32 v27, v45, 16, 1
	v_ashrrev_i32_e32 v29, 31, v28
	v_lshrrev_b32_e32 v23, 16, v23
	v_add3_u32 v27, v45, v27, s19
	v_lshlrev_b64 v[28:29], 11, v[28:29]
	v_and_or_b32 v27, v27, s20, v23
	ds_read2_b32 v[32:33], v11 offset0:16 offset1:24
	v_lshl_add_u64 v[28:29], v[30:31], 0, v[28:29]
	global_store_dwordx4 v[28:29], v[24:27], off
	ds_read2_b32 v[28:29], v11 offset0:49 offset1:57
	ds_read2_b32 v[34:35], v11 offset0:82 offset1:90
	ds_read2_b32 v[36:37], v11 offset0:115 offset1:123
	s_waitcnt lgkmcnt(3)
	v_bfe_u32 v23, v32, 16, 1
	v_add3_u32 v23, v32, v23, s19
	s_waitcnt lgkmcnt(2)
	v_bfe_u32 v24, v28, 16, 1
	ds_read2_b32 v[38:39], v11 offset0:148 offset1:156
	v_lshrrev_b32_e32 v23, 16, v23
	v_add3_u32 v24, v28, v24, s19
	ds_read2_b32 v[40:41], v11 offset0:181 offset1:189
	v_and_or_b32 v24, v24, s20, v23
	s_waitcnt lgkmcnt(3)
	v_bfe_u32 v23, v34, 16, 1
	v_add3_u32 v23, v34, v23, s19
	s_waitcnt lgkmcnt(2)
	v_bfe_u32 v25, v36, 16, 1
	ds_read2_b32 v[42:43], v11 offset0:214 offset1:222
	v_lshrrev_b32_e32 v23, 16, v23
	v_add3_u32 v25, v36, v25, s19
	ds_read2_b32 v[44:45], v11 offset0:247 offset1:255
	v_and_or_b32 v25, v25, s20, v23
	s_waitcnt lgkmcnt(3)
	v_bfe_u32 v23, v38, 16, 1
	v_add3_u32 v23, v38, v23, s19
	s_waitcnt lgkmcnt(2)
	v_bfe_u32 v26, v40, 16, 1
	v_lshrrev_b32_e32 v23, 16, v23
	v_add3_u32 v26, v40, v26, s19
	v_and_or_b32 v26, v26, s20, v23
	s_waitcnt lgkmcnt(1)
	v_bfe_u32 v23, v42, 16, 1
	v_or_b32_e32 v46, s0, v13
	v_add3_u32 v23, v42, v23, s19
	s_waitcnt lgkmcnt(0)
	v_bfe_u32 v27, v44, 16, 1
	v_ashrrev_i32_e32 v47, 31, v46
	v_lshrrev_b32_e32 v23, 16, v23
	v_add3_u32 v27, v44, v27, s19
	v_lshlrev_b64 v[46:47], 11, v[46:47]
	v_and_or_b32 v27, v27, s20, v23
	v_lshl_add_u64 v[46:47], v[30:31], 0, v[46:47]
	v_bfe_u32 v23, v33, 16, 1
	global_store_dwordx4 v[46:47], v[24:27], off
	v_add3_u32 v23, v33, v23, s19
	v_lshrrev_b32_e32 v23, 16, v23
	v_bfe_u32 v24, v29, 16, 1
	v_add3_u32 v24, v29, v24, s19
	v_and_or_b32 v24, v24, s20, v23
	v_bfe_u32 v23, v35, 16, 1
	v_add3_u32 v23, v35, v23, s19
	v_bfe_u32 v25, v37, 16, 1
	v_lshrrev_b32_e32 v23, 16, v23
	v_add3_u32 v25, v37, v25, s19
	v_and_or_b32 v25, v25, s20, v23
	v_bfe_u32 v23, v39, 16, 1
	v_add3_u32 v23, v39, v23, s19
	v_bfe_u32 v26, v41, 16, 1
	v_lshrrev_b32_e32 v23, 16, v23
	v_add3_u32 v26, v41, v26, s19
	v_and_or_b32 v26, v26, s20, v23
	v_bfe_u32 v23, v43, 16, 1
	v_or_b32_e32 v28, s0, v14
	v_add3_u32 v23, v43, v23, s19
	v_bfe_u32 v27, v45, 16, 1
	v_ashrrev_i32_e32 v29, 31, v28
	v_lshrrev_b32_e32 v23, 16, v23
	v_add3_u32 v27, v45, v27, s19
	v_lshlrev_b64 v[28:29], 11, v[28:29]
	v_and_or_b32 v27, v27, s20, v23
	v_lshl_add_u64 v[28:29], v[30:31], 0, v[28:29]
	global_store_dwordx4 v[28:29], v[24:27], off
	s_waitcnt lgkmcnt(0)
	s_branch .Ltr2_next
.Ltr2_done:
	s_mov_b64 s[6:7], s[64:65]
	s_getreg_b32 s4, hwreg(HW_REG_XCC_ID, 0, 4)
	s_waitcnt vmcnt(0)
	s_waitcnt vmcnt(0)
	s_barrier
	s_mov_b64 s[0:1], exec
	v_readlane_b32 s8, v250, 4
	v_readlane_b32 s9, v250, 5
	s_and_b64 s[8:9], s[0:1], s[8:9]
	s_mov_b64 exec, s[8:9]
	s_cbranch_execz .LBB0_877
	s_add_i32 s3, 0, 0x20160
	v_mov_b32_e32 v1, s3
	s_waitcnt vmcnt(0) expcnt(0) lgkmcnt(0)
	ds_read_b32 v3, v1
	s_add_i32 s3, 0, 0x20164
	v_mov_b32_e32 v1, s3
	ds_read_b32 v1, v1
	s_and_b32 s4, s4, 15
	s_waitcnt lgkmcnt(1)
	v_cmp_ne_u32_e32 vcc, 0, v3
	s_cbranch_vccnz .LBB0_841
	v_readlane_b32 s8, v250, 6
	v_readlane_b32 s9, v250, 7
	s_load_dwordx2 s[12:13], s[8:9], 0x4
	s_add_u32 s8, s6, 0x1000
	s_addc_u32 s9, s7, 0
	s_add_u32 s10, s6, 0x1100
	s_addc_u32 s11, s7, 0
	s_add_u32 s16, s6, 0x1200
	s_addc_u32 s17, s7, 0
	s_waitcnt lgkmcnt(0)
	s_mul_i32 s5, s12, s94
	s_add_u32 s20, s6, 0x1300
	s_mul_i32 s5, s5, s13
	s_addc_u32 s21, s7, 0
	s_mov_b32 s12, 1
	v_mov_b32_e32 v17, 0
	s_branch .LBB0_829

.LBB0_1094:
	v_readlane_b32 s0, v250, 17
	v_mov_b32_e32 v6, v0
	v_readlane_b32 s1, v250, 18
	s_andn2_b64 vcc, exec, s[0:1]
	v_readfirstlane_b32 s0, v6
	s_cbranch_vccnz .LBB0_1102
	s_sub_i32 s1, s2, s97
	s_ashr_i32 s0, s0, 6
	s_lshl_b32 s1, s1, 3
	s_add_i32 s8, s0, s1
	s_cmpk_lg_i32 s94, 0x100
	s_cbranch_scc1 .Ltr2_keep
	s_addk_i32 s8, 0x780
.Ltr2_keep:
	s_cmpk_gt_i32 s8, 0x107f
	s_cbranch_scc1 .LBB0_1102
	s_lshl_b32 s0, s0, 14
	v_and_b32_e32 v16, 31, v6
	s_add_i32 s0, s0, 0
	s_waitcnt lgkmcnt(0)
	v_mov_b32_e32 v3, 0
	v_lshlrev_b32_e32 v2, 2, v16
	v_lshl_add_u64 v[4:5], s[58:59], 0, v[2:3]
	v_add_u32_e32 v15, s0, v2
	v_lshlrev_b32_e32 v2, 3, v6
	v_and_b32_e32 v2, 56, v2
	v_bfe_u32 v10, v6, 3, 3
	v_mul_u32_u24_e32 v11, 0x84, v2
	v_lshlrev_b32_e32 v2, 1, v2
	v_lshl_add_u64 v[8:9], s[34:35], 0, v[2:3]
	v_lshlrev_b32_e32 v2, 2, v10
	v_bfe_u32 v1, v6, 5, 1
	v_add3_u32 v11, s0, v11, v2
	s_lshl_b32 s0, s94, 8
	s_lshl_b32 s3, s97, 8
	v_mul_u32_u24_e32 v17, 0x84, v1
	s_mov_b64 s[6:7], 0x2780000
	s_sub_i32 s11, s0, s3
	s_lshl_b32 s0, s8, 1
	s_sub_i32 s1, s94, s97
	s_mov_b64 s[4:5], 0xb00000
	v_lshl_add_u64 v[6:7], v[8:9], 0, s[6:7]
	s_mov_b64 s[6:7], 0x1700000
	s_add_i32 s12, s0, 0x1ea00
	s_lshl_b32 s0, s94, 4
	s_lshl_b32 s3, s97, 4
	v_add_u32_e32 v15, v15, v17
	s_lshl_b32 s9, s1, 3
	s_mov_b32 s1, 0
	v_lshl_add_u64 v[4:5], v[4:5], 0, s[4:5]
	v_or_b32_e32 v12, 8, v10
	v_or_b32_e32 v13, 16, v10
	v_or_b32_e32 v14, 24, v10
	v_lshl_add_u64 v[8:9], v[8:9], 0, s[6:7]
	s_lshl_b32 s10, s8, 5
	s_sub_i32 s13, s0, s3
	s_movk_i32 s19, 0x7fff
	s_mov_b32 s20, 0xffff0000
	v_lshlrev_b32_e32 v2, 2, v16
	s_movk_i32 s21, 0x2c00
	v_add_u32_e32 v16, 0x400, v15
	v_add_u32_e32 v17, 0x800, v15
	v_add_u32_e32 v18, 0xc00, v15
	v_add_u32_e32 v19, 0x1000, v15
	v_add_u32_e32 v20, 0x1400, v15
	v_add_u32_e32 v21, 0x1800, v15
	v_add_u32_e32 v22, 0x1c00, v15
	s_branch .LBB0_1098

.LBB0_1158:
	s_cmpk_lt_i32 s19, 0x4000
	s_waitcnt vmcnt(5)
	v_lshl_add_u64 v[18:19], v[84:85], 0, s[40:41]
	s_cselect_b64 s[6:7], -1, 0
	global_load_dwordx4 v[18:21], v[18:19], off
	s_and_b64 s[6:7], s[6:7], exec
	s_cselect_b32 s3, s27, 0xff
	s_and_b32 s3, s3, s19
	s_add_i32 s8, s3, 0x100
	s_cmpk_lt_i32 s19, 0x4000
	s_cselect_b64 s[6:7], -1, 0
	s_and_b64 s[6:7], s[6:7], exec
	s_cselect_b32 s13, s8, s3
	s_add_i32 s6, s19, 0xffffc000
	s_ashr_i32 s3, s19, 11
	s_lshr_b32 s8, s6, 8
	s_cmpk_lt_i32 s19, 0x4000
	s_cselect_b64 vcc, -1, 0
	s_and_b64 s[6:7], vcc, exec
	s_cselect_b32 s53, s3, s8
	s_add_i32 s12, s18, s19
	s_min_i32 s3, s12, 0x47ff
	s_mul_hi_i32 s7, s3, 0xc00
	s_mulk_i32 s3, 0xc00
	s_min_i32 s8, s12, 0x4000
	s_add_u32 s6, s10, s3
	s_addc_u32 s7, s11, s7
	s_lshl_b32 s3, s8, 7
	s_add_i32 s52, s22, s19
	s_and_b32 s28, s3, 0x3ff80
	s_min_i32 s3, s52, 0x47ff
	s_mul_hi_i32 s9, s3, 0xc00
	s_mulk_i32 s3, 0xc00
	s_min_i32 s24, s52, 0x4000
	s_add_u32 s8, s10, s3
	s_addc_u32 s9, s11, s9
	s_lshl_b32 s3, s24, 7
	s_waitcnt vmcnt(4)
	v_lshl_add_u64 v[22:23], v[72:73], 0, s[28:29]
	s_waitcnt lgkmcnt(5)
	v_lshl_add_u64 v[24:25], v[74:75], 0, s[28:29]
	s_and_b32 s28, s3, 0x3ff80
	s_min_i32 s3, s19, 0x4000
	s_lshl_b32 s3, s3, 7
	s_waitcnt vmcnt(2)
	v_lshl_add_u64 v[30:31], v[72:73], 0, s[28:29]
	v_lshl_add_u64 v[32:33], v[74:75], 0, s[28:29]
	s_and_b32 s28, s3, 0x3ff80
	v_lshl_add_u64 v[26:27], v[74:75], 0, s[28:29]
	global_load_dwordx4 v[90:93], v[26:27], off offset:16
	global_load_dwordx4 v[96:99], v[26:27], off
	v_lshl_add_u64 v[26:27], v[72:73], 0, s[28:29]
	global_load_dwordx4 v[100:103], v[26:27], off offset:16
	global_load_dwordx4 v[104:107], v[26:27], off
	v_lshl_add_u64 v[26:27], v[78:79], 0, s[40:41]
	s_waitcnt lgkmcnt(4)
	global_load_dwordx4 v[66:69], v[26:27], off
	s_waitcnt lgkmcnt(0)
	global_load_dwordx4 v[50:53], v[22:23], off offset:16
	global_load_dwordx4 v[46:49], v[22:23], off
	global_load_dwordx4 v[58:61], v[24:25], off offset:16
	global_load_dwordx4 v[54:57], v[24:25], off
	s_mul_hi_i32 s3, s53, 0x900
	s_mulk_i32 s53, 0x900
	s_waitcnt vmcnt(9)
	v_lshlrev_b32_e32 v108, 16, v18
	v_and_b32_e32 v110, 0xffff0000, v18
	v_lshlrev_b32_e32 v109, 16, v19
	v_and_b32_e32 v111, 0xffff0000, v19
	v_lshlrev_b32_e32 v112, 16, v20
	v_and_b32_e32 v114, 0xffff0000, v20
	v_lshlrev_b32_e32 v113, 16, v21
	v_and_b32_e32 v115, 0xffff0000, v21
	v_pk_mul_f32 v[18:19], v[108:109], v[108:109]
	v_pk_mul_f32 v[20:21], v[110:111], v[110:111]
	v_mov_b32_e32 v22, v114
	v_add_f32_e32 v18, v18, v20
	v_mov_b32_e32 v23, v112
	v_add_f32_e32 v18, v19, v18
	v_pk_mul_f32 v[22:23], v[22:23], v[22:23]
	v_add_f32_e32 v18, v21, v18
	v_mov_b32_e32 v24, v115
	v_mov_b32_e32 v25, v113
	v_add_f32_e32 v18, v23, v18
	v_pk_mul_f32 v[24:25], v[24:25], v[24:25]
	v_add_f32_e32 v18, v22, v18
	v_add_f32_e32 v18, v25, v18
	v_add_f32_e32 v22, v24, v18
	ds_bpermute_b32 v23, v1, v22
	global_load_dwordx4 v[62:65], v122, s[6:7]
	global_load_dwordx4 v[38:41], v122, s[8:9]
	global_load_dwordx4 v[42:45], v123, s[6:7] offset:1024
	global_load_dwordx4 v[18:21], v123, s[8:9] offset:1024
	s_waitcnt lgkmcnt(0)
	v_add_f32_e32 v88, v22, v23
	ds_bpermute_b32 v89, v120, v88
	global_load_dwordx4 v[26:29], v[30:31], off offset:16
	global_load_dwordx4 v[22:25], v[30:31], off
	global_load_dwordx4 v[34:37], v[32:33], off offset:16
	s_nop 0
	global_load_dwordx4 v[30:33], v[32:33], off
	s_waitcnt lgkmcnt(0)
	v_add_f32_e32 v116, v88, v89
	ds_bpermute_b32 v117, v121, v116
	s_waitcnt vmcnt(16)
	v_cndmask_b32_e32 v89, 0, v93, vcc
	s_waitcnt vmcnt(15)
	v_cndmask_b32_e32 v94, 0, v97, vcc
	v_cndmask_b32_e32 v97, 0, v98, vcc
	s_waitcnt lgkmcnt(0)
	v_add_f32_e32 v98, v116, v117
	v_fmamk_f32 v98, v98, 0x3c800000, v124
	v_rsq_f32_e32 v253, v98
	v_cndmask_b32_e32 v95, 0, v99, vcc
	s_waitcnt vmcnt(14)
	v_cndmask_b32_e32 v93, 1.0, v103, vcc
	v_cndmask_b32_e32 v88, 0, v91, vcc
	v_cndmask_b32_e32 v98, 1.0, v100, vcc
	v_cndmask_b32_e32 v91, 0, v92, vcc
	v_cndmask_b32_e32 v92, 1.0, v101, vcc
	v_cndmask_b32_e32 v99, 1.0, v102, vcc
	s_waitcnt vmcnt(13)
	v_cndmask_b32_e32 v101, 1.0, v107, vcc
	v_cndmask_b32_e32 v90, 0, v90, vcc
	v_cndmask_b32_e32 v96, 0, v96, vcc
	s_waitcnt vmcnt(12)
	v_and_b32_e32 v118, 0xffff0000, v68
	v_mov_b32_e32 v126, v118
	v_cndmask_b32_e32 v102, 1.0, v104, vcc
	v_and_b32_e32 v119, 0xffff0000, v69
	v_cndmask_b32_e32 v100, 1.0, v105, vcc
	v_cndmask_b32_e32 v103, 1.0, v106, vcc
	v_mov_b32_e32 v128, v119
	v_mov_b32_e32 v104, v253
	v_pk_mul_f32 v[106:107], v[104:105], v[108:109] op_sel_hi:[0,1]
	v_pk_mul_f32 v[106:107], v[86:87], v[106:107]
	v_pk_mul_f32 v[110:111], v[104:105], v[110:111] op_sel_hi:[0,1]
	ds_bpermute_b32 v108, v121, v106
	ds_bpermute_b32 v109, v121, v107
	v_pk_mul_f32 v[110:111], v[4:5], v[110:111]
	ds_bpermute_b32 v116, v121, v110
	ds_bpermute_b32 v117, v121, v111
	v_pk_mul_f32 v[106:107], v[102:103], v[106:107]
	s_waitcnt lgkmcnt(2)
	v_pk_mul_f32 v[108:109], v[70:71], v[108:109]
	s_nop 0
	v_pk_fma_f32 v[106:107], v[96:97], v[108:109], v[106:107]
	v_pk_mul_f32 v[108:109], v[100:101], v[110:111]
	s_waitcnt lgkmcnt(0)
	v_pk_mul_f32 v[110:111], v[70:71], v[116:117]
	v_lshlrev_b32_e32 v116, 16, v68
	v_pk_fma_f32 v[108:109], v[94:95], v[110:111], v[108:109]
	v_pk_mul_f32 v[110:111], v[104:105], v[112:113] op_sel_hi:[0,1]
	v_pk_mul_f32 v[110:111], v[6:7], v[110:111]
	ds_bpermute_b32 v112, v121, v110
	ds_bpermute_b32 v113, v121, v111
	v_pk_mul_f32 v[104:105], v[104:105], v[114:115] op_sel_hi:[0,1]
	v_pk_mul_f32 v[104:105], v[12:13], v[104:105]
	ds_bpermute_b32 v114, v121, v104
	ds_bpermute_b32 v115, v121, v105
	s_waitcnt lgkmcnt(2)
	v_pk_mul_f32 v[112:113], v[70:71], v[112:113]
	v_pk_mul_f32 v[108:109], v[108:109], s[48:49] op_sel_hi:[1,0]
	v_pk_mul_f32 v[112:113], v[90:91], v[112:113]
	v_mov_b32_e32 v127, v116
	v_pk_fma_f32 v[110:111], v[98:99], v[110:111], v[112:113]
	s_waitcnt lgkmcnt(0)
	v_pk_mul_f32 v[112:113], v[70:71], v[114:115]
	v_lshlrev_b32_e32 v117, 16, v69
	v_pk_mul_f32 v[112:113], v[88:89], v[112:113]
	v_pk_mul_f32 v[126:127], v[126:127], v[126:127]
	v_pk_fma_f32 v[104:105], v[92:93], v[104:105], v[112:113]
	v_bfe_u32 v112, v109, 16, 1
	v_pk_mul_f32 v[104:105], v[104:105], s[48:49] op_sel_hi:[1,0]
	v_bfe_u32 v113, v108, 16, 1
	v_bfe_u32 v114, v105, 16, 1
	v_bfe_u32 v115, v104, 16, 1
	v_add3_u32 v132, v108, v113, s56
	v_add3_u32 v133, v109, v112, s56
	v_lshlrev_b32_e32 v109, 16, v67
	v_lshlrev_b32_e32 v108, 16, v66
	v_and_b32_e32 v113, 0xffff0000, v67
	v_and_b32_e32 v112, 0xffff0000, v66
	v_add3_u32 v130, v104, v115, s56
	v_add3_u32 v131, v105, v114, s56
	v_pk_mul_f32 v[104:105], v[108:109], v[108:109]
	v_pk_mul_f32 v[114:115], v[112:113], v[112:113]
	v_mov_b32_e32 v129, v117
	v_add_f32_e32 v104, v104, v114
	v_add_f32_e32 v104, v105, v104
	v_add_f32_e32 v104, v115, v104
	v_add_f32_e32 v104, v127, v104
	v_pk_mul_f32 v[128:129], v[128:129], v[128:129]
	v_add_f32_e32 v104, v126, v104
	v_add_f32_e32 v104, v129, v104
	v_add_f32_e32 v104, v128, v104
	ds_bpermute_b32 v105, v1, v104
	v_pk_mul_f32 v[110:111], v[110:111], s[48:49] op_sel_hi:[1,0]
	v_pk_mul_f32 v[106:107], v[106:107], s[48:49] op_sel_hi:[1,0]
	v_bfe_u32 v114, v110, 16, 1
	v_bfe_u32 v115, v111, 16, 1
	s_waitcnt lgkmcnt(0)
	v_add_f32_e32 v104, v104, v105
	ds_bpermute_b32 v105, v120, v104
	v_add3_u32 v110, v110, v114, s56
	v_add3_u32 v111, v111, v115, s56
	v_bfe_u32 v126, v106, 16, 1
	v_bfe_u32 v127, v107, 16, 1
	s_waitcnt lgkmcnt(0)
	v_add_f32_e32 v104, v104, v105
	ds_bpermute_b32 v105, v121, v104
	v_add3_u32 v106, v106, v126, s56
	v_add3_u32 v107, v107, v127, s56
	v_lshrrev_b32_e32 v106, 16, v106
	v_lshrrev_b32_e32 v111, 16, v111
	s_waitcnt lgkmcnt(0)
	v_add_f32_e32 v104, v104, v105
	v_fmamk_f32 v104, v104, 0x3c800000, v124
	v_rsq_f32_e32 v254, v104
	v_lshrrev_b32_e32 v107, 16, v107
	v_lshrrev_b32_e32 v110, 16, v110
	v_and_or_b32 v104, v132, s33, v106
	v_and_or_b32 v105, v133, s33, v107
	v_and_or_b32 v107, v131, s33, v111
	v_and_or_b32 v106, v130, s33, v110
	v_lshl_add_u64 v[110:111], v[14:15], 0, s[44:45]
	global_store_dwordx4 v[110:111], v[104:107], off
	s_add_u32 s6, s53, s13
	s_addc_u32 s7, s3, 0
	v_mov_b32_e32 v126, v254
	v_pk_mul_f32 v[104:105], v[126:127], v[108:109] op_sel_hi:[0,1]
	v_pk_mul_f32 v[108:109], v[126:127], v[112:113] op_sel_hi:[0,1]
	v_pk_mul_f32 v[114:115], v[8:9], v[108:109]
	v_pk_mul_f32 v[108:109], v[126:127], v[116:117] op_sel_hi:[0,1]
	v_pk_mul_f32 v[116:117], v[126:127], v[118:119] op_sel_hi:[0,1]
	v_pk_mul_f32 v[106:107], v[2:3], v[104:105]
	v_pk_mul_f32 v[108:109], v[10:11], v[108:109]
	v_pk_mul_f32 v[116:117], v[16:17], v[116:117]
	ds_bpermute_b32 v104, v121, v106
	ds_bpermute_b32 v110, v121, v114
	ds_bpermute_b32 v105, v121, v107
	ds_bpermute_b32 v111, v121, v115
	ds_bpermute_b32 v112, v121, v108
	ds_bpermute_b32 v118, v121, v116
	ds_bpermute_b32 v113, v121, v109
	ds_bpermute_b32 v119, v121, v117
	s_lshl_b64 s[6:7], s[6:7], 7
	s_and_saveexec_b64 s[8:9], s[0:1]
	s_xor_b64 s[8:9], exec, s[8:9]
	s_cbranch_execnz .LBB0_1162
	s_andn2_saveexec_b64 s[8:9], s[8:9]
	s_cbranch_execnz .LBB0_1165

.LBB0_1166:
	s_waitcnt vmcnt(8)
	v_lshlrev_b32_e32 v66, 16, v62
	v_and_b32_e32 v68, 0xffff0000, v62
	v_lshlrev_b32_e32 v67, 16, v63
	v_and_b32_e32 v69, 0xffff0000, v63
	v_pk_mul_f32 v[62:63], v[66:67], v[66:67]
	v_pk_mul_f32 v[90:91], v[68:69], v[68:69]
	v_lshlrev_b32_e32 v88, 16, v64
	v_and_b32_e32 v64, 0xffff0000, v64
	v_add_f32_e32 v62, v62, v90
	v_mov_b32_e32 v92, v64
	v_mov_b32_e32 v93, v88
	v_add_f32_e32 v62, v63, v62
	v_lshlrev_b32_e32 v89, 16, v65
	v_and_b32_e32 v65, 0xffff0000, v65
	v_pk_mul_f32 v[92:93], v[92:93], v[92:93]
	v_add_f32_e32 v62, v91, v62
	v_mov_b32_e32 v94, v65
	v_mov_b32_e32 v95, v89
	v_add_f32_e32 v62, v93, v62
	v_pk_mul_f32 v[94:95], v[94:95], v[94:95]
	v_add_f32_e32 v62, v92, v62
	v_add_f32_e32 v62, v95, v62
	v_add_f32_e32 v90, v94, v62
	ds_bpermute_b32 v91, v1, v90
	s_cmpk_lt_i32 s12, 0x4000
	s_cselect_b64 s[6:7], -1, 0
	s_and_b64 s[6:7], s[6:7], exec
	s_cselect_b32 s3, s27, 0xff
	s_waitcnt lgkmcnt(0)
	v_add_f32_e32 v90, v90, v91
	ds_bpermute_b32 v91, v120, v90
	s_and_b32 s3, s3, s12
	s_add_i32 s8, s3, 0x100
	s_cmpk_lt_i32 s12, 0x4000
	s_cselect_b64 s[6:7], -1, 0
	s_waitcnt lgkmcnt(0)
	v_add_f32_e32 v90, v90, v91
	s_and_b64 s[6:7], s[6:7], exec
	ds_bpermute_b32 v91, v121, v90
	s_cselect_b32 s13, s8, s3
	s_add_i32 s6, s12, 0xffffc000
	s_ashr_i32 s3, s12, 11
	s_lshr_b32 s8, s6, 8
	s_cmpk_lt_i32 s12, 0x4000
	s_cselect_b64 vcc, -1, 0
	v_cndmask_b32_e32 v63, 0, v61, vcc
	v_cndmask_b32_e32 v61, 0, v57, vcc
	v_cndmask_b32_e32 v57, 0, v56, vcc
	v_cndmask_b32_e32 v56, 0, v54, vcc
	v_cndmask_b32_e32 v54, 1.0, v51, vcc
	s_waitcnt lgkmcnt(0)
	v_add_f32_e32 v51, v90, v91
	s_and_b64 s[6:7], vcc, exec
	v_fmamk_f32 v51, v51, 0x3c800000, v124
	v_rsq_f32_e32 v251, v51
	v_cndmask_b32_e32 v62, 0, v59, vcc
	v_cndmask_b32_e32 v59, 0, v60, vcc
	v_cndmask_b32_e32 v60, 0, v55, vcc
	v_cndmask_b32_e32 v55, 1.0, v53, vcc
	s_cselect_b32 s12, s3, s8
	v_cndmask_b32_e32 v58, 0, v58, vcc
	v_cndmask_b32_e32 v53, 1.0, v49, vcc
	v_cndmask_b32_e32 v51, 1.0, v52, vcc
	v_cndmask_b32_e32 v50, 1.0, v50, vcc
	v_cndmask_b32_e32 v46, 1.0, v46, vcc
	s_waitcnt vmcnt(6)
	v_and_b32_e32 v94, 0xffff0000, v44
	v_mov_b32_e32 v96, v94
	v_cndmask_b32_e32 v52, 1.0, v47, vcc
	v_cndmask_b32_e32 v47, 1.0, v48, vcc
	v_and_b32_e32 v95, 0xffff0000, v45
	v_mov_b32_e32 v98, v95
	s_mul_hi_i32 s3, s12, 0x900
	v_mov_b32_e32 v48, v251
	v_pk_mul_f32 v[66:67], v[48:49], v[66:67] op_sel_hi:[0,1]
	v_pk_mul_f32 v[66:67], v[86:87], v[66:67]
	v_pk_mul_f32 v[68:69], v[48:49], v[68:69] op_sel_hi:[0,1]
	ds_bpermute_b32 v90, v121, v66
	ds_bpermute_b32 v91, v121, v67
	v_pk_mul_f32 v[68:69], v[4:5], v[68:69]
	ds_bpermute_b32 v92, v121, v68
	ds_bpermute_b32 v93, v121, v69
	v_pk_mul_f32 v[88:89], v[48:49], v[88:89] op_sel_hi:[0,1]
	v_pk_mul_f32 v[48:49], v[48:49], v[64:65] op_sel_hi:[0,1]
	v_pk_mul_f32 v[48:49], v[12:13], v[48:49]
	v_pk_mul_f32 v[66:67], v[46:47], v[66:67]
	s_waitcnt lgkmcnt(2)
	v_pk_mul_f32 v[90:91], v[70:71], v[90:91]
	ds_bpermute_b32 v64, v121, v48
	ds_bpermute_b32 v65, v121, v49
	v_pk_fma_f32 v[66:67], v[56:57], v[90:91], v[66:67]
	v_pk_mul_f32 v[68:69], v[52:53], v[68:69]
	s_waitcnt lgkmcnt(2)
	v_pk_mul_f32 v[90:91], v[70:71], v[92:93]
	v_pk_mul_f32 v[88:89], v[6:7], v[88:89]
	v_pk_fma_f32 v[68:69], v[60:61], v[90:91], v[68:69]
	ds_bpermute_b32 v90, v121, v88
	ds_bpermute_b32 v91, v121, v89
	s_waitcnt lgkmcnt(2)
	v_pk_mul_f32 v[64:65], v[70:71], v[64:65]
	v_pk_mul_f32 v[68:69], v[68:69], s[48:49] op_sel_hi:[1,0]
	v_pk_mul_f32 v[64:65], v[62:63], v[64:65]
	v_lshlrev_b32_e32 v92, 16, v44
	s_waitcnt lgkmcnt(0)
	v_pk_mul_f32 v[90:91], v[70:71], v[90:91]
	v_pk_fma_f32 v[48:49], v[54:55], v[48:49], v[64:65]
	v_pk_mul_f32 v[90:91], v[58:59], v[90:91]
	v_pk_mul_f32 v[48:49], v[48:49], s[48:49] op_sel_hi:[1,0]
	v_pk_fma_f32 v[88:89], v[50:51], v[88:89], v[90:91]
	v_bfe_u32 v64, v69, 16, 1
	v_bfe_u32 v65, v68, 16, 1
	v_bfe_u32 v90, v49, 16, 1
	v_bfe_u32 v91, v48, 16, 1
	v_add3_u32 v100, v48, v91, s56
	v_add3_u32 v101, v49, v90, s56
	v_add3_u32 v102, v68, v65, s56
	v_add3_u32 v103, v69, v64, s56
	v_lshlrev_b32_e32 v49, 16, v43
	v_lshlrev_b32_e32 v48, 16, v42
	v_and_b32_e32 v69, 0xffff0000, v43
	v_and_b32_e32 v68, 0xffff0000, v42
	v_pk_mul_f32 v[64:65], v[48:49], v[48:49]
	v_pk_mul_f32 v[90:91], v[68:69], v[68:69]
	v_mov_b32_e32 v97, v92
	v_add_f32_e32 v64, v64, v90
	v_add_f32_e32 v64, v65, v64
	v_lshlrev_b32_e32 v93, 16, v45
	v_pk_mul_f32 v[96:97], v[96:97], v[96:97]
	v_add_f32_e32 v64, v91, v64
	v_mov_b32_e32 v99, v93
	v_add_f32_e32 v64, v97, v64
	v_pk_mul_f32 v[98:99], v[98:99], v[98:99]
	v_add_f32_e32 v64, v96, v64
	v_add_f32_e32 v64, v99, v64
	v_add_f32_e32 v64, v98, v64
	ds_bpermute_b32 v65, v1, v64
	v_pk_mul_f32 v[88:89], v[88:89], s[48:49] op_sel_hi:[1,0]
	v_pk_mul_f32 v[66:67], v[66:67], s[48:49] op_sel_hi:[1,0]
	v_bfe_u32 v90, v88, 16, 1
	v_bfe_u32 v91, v89, 16, 1
	s_waitcnt lgkmcnt(0)
	v_add_f32_e32 v64, v64, v65
	ds_bpermute_b32 v65, v120, v64
	v_add3_u32 v88, v88, v90, s56
	v_add3_u32 v89, v89, v91, s56
	v_bfe_u32 v96, v66, 16, 1
	v_bfe_u32 v97, v67, 16, 1
	s_waitcnt lgkmcnt(0)
	v_add_f32_e32 v64, v64, v65
	ds_bpermute_b32 v65, v121, v64
	v_add3_u32 v66, v66, v96, s56
	v_add3_u32 v67, v67, v97, s56
	v_lshrrev_b32_e32 v66, 16, v66
	v_lshrrev_b32_e32 v89, 16, v89
	s_waitcnt lgkmcnt(0)
	v_add_f32_e32 v64, v64, v65
	v_fmamk_f32 v64, v64, 0x3c800000, v124
	v_rsq_f32_e32 v252, v64
	v_lshrrev_b32_e32 v67, 16, v67
	v_lshrrev_b32_e32 v88, 16, v88
	v_and_or_b32 v64, v102, s33, v66
	v_and_or_b32 v65, v103, s33, v67
	v_and_or_b32 v67, v101, s33, v89
	s_mulk_i32 s12, 0x900
	v_and_or_b32 v66, v100, s33, v88
	v_lshl_add_u64 v[88:89], v[14:15], 0, s[38:39]
	global_store_dwordx4 v[88:89], v[64:67], off
	s_add_u32 s6, s12, s13
	s_addc_u32 s7, s3, 0
	v_mov_b32_e32 v96, v252
	v_pk_mul_f32 v[66:67], v[96:97], v[68:69] op_sel_hi:[0,1]
	v_pk_mul_f32 v[48:49], v[96:97], v[48:49] op_sel_hi:[0,1]
	v_pk_mul_f32 v[90:91], v[8:9], v[66:67]
	v_pk_mul_f32 v[66:67], v[96:97], v[92:93] op_sel_hi:[0,1]
	v_pk_mul_f32 v[92:93], v[96:97], v[94:95] op_sel_hi:[0,1]
	v_pk_mul_f32 v[64:65], v[2:3], v[48:49]
	v_pk_mul_f32 v[66:67], v[10:11], v[66:67]
	v_pk_mul_f32 v[92:93], v[16:17], v[92:93]
	ds_bpermute_b32 v48, v121, v64
	ds_bpermute_b32 v68, v121, v90
	ds_bpermute_b32 v49, v121, v65
	ds_bpermute_b32 v69, v121, v91
	ds_bpermute_b32 v88, v121, v66
	ds_bpermute_b32 v94, v121, v92
	ds_bpermute_b32 v89, v121, v67
	ds_bpermute_b32 v95, v121, v93
	s_lshl_b64 s[6:7], s[6:7], 7
	s_and_saveexec_b64 s[8:9], s[0:1]
	s_xor_b64 s[8:9], exec, s[8:9]
	s_cbranch_execz .LBB0_1170
	s_and_saveexec_b64 s[54:55], s[4:5]
	s_cbranch_execz .LBB0_1169
	v_lshl_add_u64 v[46:47], s[6:7], 1, v[80:81]
	global_store_dwordx4 v[46:47], v[42:45], off offset:-256

.LBB0_1173:
	s_waitcnt vmcnt(6)
	v_lshlrev_b32_e32 v42, 16, v38
	v_and_b32_e32 v44, 0xffff0000, v38
	v_lshlrev_b32_e32 v43, 16, v39
	v_and_b32_e32 v45, 0xffff0000, v39
	v_pk_mul_f32 v[38:39], v[42:43], v[42:43]
	s_waitcnt lgkmcnt(5)
	v_pk_mul_f32 v[48:49], v[44:45], v[44:45]
	v_lshlrev_b32_e32 v46, 16, v40
	v_and_b32_e32 v40, 0xffff0000, v40
	v_add_f32_e32 v38, v38, v48
	v_mov_b32_e32 v50, v40
	v_mov_b32_e32 v51, v46
	v_add_f32_e32 v38, v39, v38
	v_lshlrev_b32_e32 v47, 16, v41
	v_and_b32_e32 v41, 0xffff0000, v41
	v_pk_mul_f32 v[50:51], v[50:51], v[50:51]
	v_add_f32_e32 v38, v49, v38
	v_mov_b32_e32 v52, v41
	v_mov_b32_e32 v53, v47
	v_add_f32_e32 v38, v51, v38
	v_pk_mul_f32 v[52:53], v[52:53], v[52:53]
	v_add_f32_e32 v38, v50, v38
	v_add_f32_e32 v38, v53, v38
	v_add_f32_e32 v48, v52, v38
	ds_bpermute_b32 v49, v1, v48
	s_cmpk_lt_i32 s52, 0x4000
	s_cselect_b64 s[6:7], -1, 0
	s_and_b64 s[6:7], s[6:7], exec
	s_cselect_b32 s3, s27, 0xff
	s_waitcnt lgkmcnt(0)
	v_add_f32_e32 v48, v48, v49
	ds_bpermute_b32 v49, v120, v48
	s_and_b32 s3, s3, s52
	s_add_i32 s8, s3, 0x100
	s_cmpk_lt_i32 s52, 0x4000
	s_cselect_b64 s[6:7], -1, 0
	s_waitcnt lgkmcnt(0)
	v_add_f32_e32 v48, v48, v49
	s_and_b64 s[6:7], s[6:7], exec
	ds_bpermute_b32 v49, v121, v48
	s_cselect_b32 s12, s8, s3
	s_add_i32 s6, s52, 0xffffc000
	s_ashr_i32 s3, s52, 11
	s_lshr_b32 s8, s6, 8
	s_cmpk_lt_i32 s52, 0x4000
	s_cselect_b64 vcc, -1, 0
	s_waitcnt vmcnt(2)
	v_cndmask_b32_e32 v39, 0, v37, vcc
	s_waitcnt vmcnt(1)
	v_cndmask_b32_e32 v37, 0, v33, vcc
	v_cndmask_b32_e32 v33, 0, v32, vcc
	v_cndmask_b32_e32 v32, 0, v30, vcc
	v_cndmask_b32_e32 v30, 1.0, v27, vcc
	s_waitcnt lgkmcnt(0)
	v_add_f32_e32 v27, v48, v49
	s_and_b64 s[6:7], vcc, exec
	v_fmamk_f32 v27, v27, 0x3c800000, v124
	v_rsq_f32_e32 v253, v27
	v_cndmask_b32_e32 v38, 0, v35, vcc
	v_cndmask_b32_e32 v35, 0, v36, vcc
	v_cndmask_b32_e32 v36, 0, v31, vcc
	v_cndmask_b32_e32 v31, 1.0, v29, vcc
	s_cselect_b32 s13, s3, s8
	v_cndmask_b32_e32 v34, 0, v34, vcc
	v_cndmask_b32_e32 v29, 1.0, v25, vcc
	v_cndmask_b32_e32 v27, 1.0, v28, vcc
	v_cndmask_b32_e32 v26, 1.0, v26, vcc
	v_cndmask_b32_e32 v22, 1.0, v22, vcc
	v_and_b32_e32 v52, 0xffff0000, v20
	v_mov_b32_e32 v54, v52
	v_cndmask_b32_e32 v28, 1.0, v23, vcc
	v_cndmask_b32_e32 v23, 1.0, v24, vcc
	v_and_b32_e32 v53, 0xffff0000, v21
	v_mov_b32_e32 v56, v53
	s_ashr_i32 s53, s52, 31
	v_mov_b32_e32 v24, v253
	v_pk_mul_f32 v[42:43], v[24:25], v[42:43] op_sel_hi:[0,1]
	v_pk_mul_f32 v[42:43], v[86:87], v[42:43]
	v_pk_mul_f32 v[44:45], v[24:25], v[44:45] op_sel_hi:[0,1]
	ds_bpermute_b32 v48, v121, v42
	ds_bpermute_b32 v49, v121, v43
	v_pk_mul_f32 v[44:45], v[4:5], v[44:45]
	ds_bpermute_b32 v50, v121, v44
	ds_bpermute_b32 v51, v121, v45
	v_pk_mul_f32 v[46:47], v[24:25], v[46:47] op_sel_hi:[0,1]
	v_pk_mul_f32 v[24:25], v[24:25], v[40:41] op_sel_hi:[0,1]
	v_pk_mul_f32 v[24:25], v[12:13], v[24:25]
	v_pk_mul_f32 v[42:43], v[22:23], v[42:43]
	s_waitcnt lgkmcnt(2)
	v_pk_mul_f32 v[48:49], v[70:71], v[48:49]
	ds_bpermute_b32 v40, v121, v24
	ds_bpermute_b32 v41, v121, v25
	v_pk_fma_f32 v[42:43], v[32:33], v[48:49], v[42:43]
	v_pk_mul_f32 v[44:45], v[28:29], v[44:45]
	s_waitcnt lgkmcnt(2)
	v_pk_mul_f32 v[48:49], v[70:71], v[50:51]
	v_pk_mul_f32 v[46:47], v[6:7], v[46:47]
	v_pk_fma_f32 v[44:45], v[36:37], v[48:49], v[44:45]
	ds_bpermute_b32 v48, v121, v46
	ds_bpermute_b32 v49, v121, v47
	s_waitcnt lgkmcnt(2)
	v_pk_mul_f32 v[40:41], v[70:71], v[40:41]
	v_pk_mul_f32 v[44:45], v[44:45], s[48:49] op_sel_hi:[1,0]
	v_pk_mul_f32 v[40:41], v[38:39], v[40:41]
	v_lshlrev_b32_e32 v50, 16, v20
	s_waitcnt lgkmcnt(0)
	v_pk_mul_f32 v[48:49], v[70:71], v[48:49]
	v_pk_fma_f32 v[24:25], v[30:31], v[24:25], v[40:41]
	v_pk_mul_f32 v[48:49], v[34:35], v[48:49]
	v_pk_mul_f32 v[24:25], v[24:25], s[48:49] op_sel_hi:[1,0]
	v_pk_fma_f32 v[46:47], v[26:27], v[46:47], v[48:49]
	v_bfe_u32 v40, v45, 16, 1
	v_bfe_u32 v41, v44, 16, 1
	v_bfe_u32 v48, v25, 16, 1
	v_bfe_u32 v49, v24, 16, 1
	v_add3_u32 v58, v24, v49, s56
	v_add3_u32 v59, v25, v48, s56
	v_add3_u32 v60, v44, v41, s56
	v_add3_u32 v61, v45, v40, s56
	v_lshlrev_b32_e32 v25, 16, v19
	v_lshlrev_b32_e32 v24, 16, v18
	v_and_b32_e32 v45, 0xffff0000, v19
	v_and_b32_e32 v44, 0xffff0000, v18
	v_pk_mul_f32 v[40:41], v[24:25], v[24:25]
	v_pk_mul_f32 v[48:49], v[44:45], v[44:45]
	v_mov_b32_e32 v55, v50
	v_add_f32_e32 v40, v40, v48
	v_add_f32_e32 v40, v41, v40
	v_lshlrev_b32_e32 v51, 16, v21
	v_pk_mul_f32 v[54:55], v[54:55], v[54:55]
	v_add_f32_e32 v40, v49, v40
	v_mov_b32_e32 v57, v51
	v_add_f32_e32 v40, v55, v40
	v_pk_mul_f32 v[56:57], v[56:57], v[56:57]
	v_add_f32_e32 v40, v54, v40
	v_add_f32_e32 v40, v57, v40
	v_add_f32_e32 v40, v56, v40
	ds_bpermute_b32 v41, v1, v40
	v_pk_mul_f32 v[42:43], v[42:43], s[48:49] op_sel_hi:[1,0]
	v_pk_mul_f32 v[46:47], v[46:47], s[48:49] op_sel_hi:[1,0]
	v_bfe_u32 v48, v42, 16, 1
	v_bfe_u32 v49, v43, 16, 1
	s_waitcnt lgkmcnt(0)
	v_add_f32_e32 v40, v40, v41
	ds_bpermute_b32 v41, v120, v40
	v_add3_u32 v42, v42, v48, s56
	v_add3_u32 v43, v43, v49, s56
	v_bfe_u32 v62, v46, 16, 1
	v_bfe_u32 v63, v47, 16, 1
	s_waitcnt lgkmcnt(0)
	v_add_f32_e32 v48, v40, v41
	ds_bpermute_b32 v49, v121, v48
	v_lshrrev_b32_e32 v40, 16, v42
	v_lshrrev_b32_e32 v41, 16, v43
	v_add3_u32 v46, v46, v62, s56
	v_add3_u32 v47, v47, v63, s56
	s_waitcnt lgkmcnt(0)
	v_add_f32_e32 v42, v48, v49
	v_fmamk_f32 v42, v42, 0x3c800000, v124
	v_rsq_f32_e32 v254, v42
	v_lshrrev_b32_e32 v46, 16, v46
	v_lshrrev_b32_e32 v47, 16, v47
	v_and_or_b32 v42, v58, s33, v46
	v_and_or_b32 v43, v59, s33, v47
	v_and_or_b32 v41, v61, s33, v41
	v_and_or_b32 v40, v60, s33, v40
	s_mul_hi_i32 s3, s13, 0x900
	s_mulk_i32 s13, 0x900
	s_lshl_b64 s[6:7], s[52:53], 11
	v_lshl_add_u64 v[46:47], v[76:77], 0, s[6:7]
	global_store_dwordx4 v[46:47], v[40:43], off
	s_add_u32 s6, s13, s12
	s_addc_u32 s7, s3, 0
	v_mov_b32_e32 v54, v254
	v_pk_mul_f32 v[42:43], v[54:55], v[44:45] op_sel_hi:[0,1]
	v_pk_mul_f32 v[24:25], v[54:55], v[24:25] op_sel_hi:[0,1]
	v_pk_mul_f32 v[48:49], v[8:9], v[42:43]
	v_pk_mul_f32 v[42:43], v[54:55], v[50:51] op_sel_hi:[0,1]
	v_pk_mul_f32 v[50:51], v[54:55], v[52:53] op_sel_hi:[0,1]
	v_pk_mul_f32 v[40:41], v[2:3], v[24:25]
	v_pk_mul_f32 v[42:43], v[10:11], v[42:43]
	v_pk_mul_f32 v[50:51], v[16:17], v[50:51]
	ds_bpermute_b32 v24, v121, v40
	ds_bpermute_b32 v44, v121, v48
	ds_bpermute_b32 v25, v121, v41
	ds_bpermute_b32 v45, v121, v49
	ds_bpermute_b32 v46, v121, v42
	ds_bpermute_b32 v52, v121, v50
	ds_bpermute_b32 v47, v121, v43
	ds_bpermute_b32 v53, v121, v51
	s_lshl_b64 s[6:7], s[6:7], 7
	s_and_saveexec_b64 s[8:9], s[0:1]
	s_xor_b64 s[8:9], exec, s[8:9]
	s_cbranch_execz .LBB0_1177
	s_and_saveexec_b64 s[52:53], s[4:5]
	s_cbranch_execz .LBB0_1176
	v_lshl_add_u64 v[22:23], s[6:7], 1, v[80:81]
	global_store_dwordx4 v[22:23], v[18:21], off offset:-256
